# scan: decay vector w loaded straight from global memory into registers 7 steps ahead instead of staging through LDS (one LDS read per step less)
# speedup vs baseline: 1.0064x; 1.0064x over previous
; __device__ __forceinline__ void rwkv_scan2_item(const Params& p, int item, char* ldsraw) {
;     ...
;   auto load = [&](int chunk) {
;     const size_t base = (size_t)bh * S + chunk * 16 + st;
;     pw = *(const f32x4*)(RW + base * 64 + part * 4);
;     const bf16_t* rb = RB + base * 320;
;     pkk = *(const u32x2*)(rb + part * 4); pkka = *(const u32x2*)(rb + 64 + part * 4);
;     pk = *(const u32x2*)(rb + 128 + part * 4); pwr = *(const u32x2*)(rb + 192 + part * 4);
;     pv = rb[256 + r16 * 16 + part];
;     pc = (part < 2) ? RC[base * 4 + part] : 0.f;
;   };
;   auto store = [&](int bi) {
;     float* d = buf + bi * CH + st * STEP;
;     *(f32x4*)(d + part * 4) = pw;
;     *(f32x4*)(d + 64 + part * 4) = (f32x4){bflo(pkk[0]), bfhi(pkk[0]), bflo(pkk[1]), bfhi(pkk[1])};
;     *(f32x4*)(d + 128 + part * 4) = (f32x4){bflo(pkka[0]), bfhi(pkka[0]), bflo(pkka[1]), bfhi(pkka[1])};
;     *(f32x4*)(d + 192 + part * 4) = (f32x4){bflo(pk[0]), bfhi(pk[0]), bflo(pk[1]), bfhi(pk[1])};
;     *(f32x4*)(d + 256 + part * 4) = (f32x4){bflo(pwr[0]), bfhi(pwr[0]), bflo(pwr[1]), bfhi(pwr[1])};
;     d[320 + part] = ident ? 0.f : bf2f(pv);
;     if (part < 2) d[336 + part] = pc;
;   };
;   load(c0); store(0); __syncthreads();
;     ...
;   for (int c = 0; c <= 128; c++) {
;     if (c + 1 < 128) load(c0 + c + 1);
;     const int bprev = (bi == 0) ? 2 : bi - 1, bnext = (bi == 2) ? 0 : bi + 1;
;     if (!isY) {
;       if (c < 128) {
;         const float* d = buf + bi * CH + jl * 4;
;         const float* dvp = buf + bi * CH + 320 + row8;
;         f32x4 nw, nkk, nkka, nk; float nvA, nvB;
;     ...
;         R_LOAD(0)
;         float sakA = 0.f, sakB = 0.f;
; #pragma unroll
;         for (int q = 0; q < 16; q++) {
;           const f32x4 cw = nw, ckk = nkk, ckka = nkka, ck = nk; const float cvA = nvA, cvB = nvB;
;           if (q < 15) R_LOAD(q + 1)
;           __builtin_amdgcn_sched_barrier(0);
;           float mA0 = mul_s(a0, ckk.x), mA1 = mul_s(a2, ckk.z), mB0 = mul_s(b0, ckk.x), mB1 = mul_s(b2, ckk.z);
;           mA0 = fma_s(a1, ckk.y, mA0); mA1 = fma_s(a3, ckk.w, mA1); mB0 = fma_s(b1, ckk.y, mB0); mB1 = fma_s(b3, ckk.w, mB1);
;           float psA = add_s(mA0, mA1), psB = add_s(mB0, mB1);
;           psA = row16_sum(psA); psB = row16_sum(psB);
;           { const float t0 = fnma_s(psA, ckka.x, mul_s(cvA, ck.x)), t1 = fnma_s(psA, ckka.y, mul_s(cvA, ck.y));
.Lsc_noident:
	global_load_dwordx2 v[24:25], v13, s[26:27]
	global_load_dwordx2 v[26:27], v13, s[26:27] offset:128
	global_load_dwordx2 v[28:29], v13, s[26:27] offset:256
	global_load_dwordx2 v[30:31], v13, s[26:27] offset:384
	global_load_ushort v32, v14, s[26:27]
	global_load_dwordx2 v[34:35], v15, s[28:29]
	s_waitcnt vmcnt(0)
	v_lshlrev_b32_e32 v36, 16, v24
	v_lshlrev_b32_e32 v37, 16, v30
	v_and_b32_e32 v38, 0xffff0000, v24
	v_and_b32_e32 v39, 0xffff0000, v30
	ds_write_b128 v2, v[36:39] offset:256
	v_lshlrev_b32_e32 v40, 16, v25
	v_lshlrev_b32_e32 v41, 16, v31
	v_and_b32_e32 v42, 0xffff0000, v25
	v_and_b32_e32 v43, 0xffff0000, v31
	ds_write_b128 v2, v[40:43] offset:512
	v_lshlrev_b32_e32 v44, 16, v26
	v_and_b32_e32 v45, 0xffff0000, v26
	v_lshlrev_b32_e32 v46, 16, v27
	v_and_b32_e32 v47, 0xffff0000, v27
	ds_write_b128 v2, v[44:47] offset:768
	v_lshlrev_b32_e32 v48, 16, v28
	v_and_b32_e32 v49, 0xffff0000, v28
	v_lshlrev_b32_e32 v50, 16, v29
	v_and_b32_e32 v51, 0xffff0000, v29
	ds_write_b128 v2, v[48:51] offset:1024
	v_lshlrev_b32_e32 v52, 16, v32
	s_cmp_eq_u32 s41, 2
	s_cselect_b32 s2, 0, -1
	v_and_b32_e32 v52, s2, v52
	ds_write_b32 v8, v52 offset:0
	s_mov_b32 s2, 0x00010001
	s_mov_b32 s3, 0x00010001
	s_mov_b64 exec, s[2:3]
	ds_write_b64 v9, v[34:35] offset:0
	s_mov_b64 exec, -1
	s_add_u32 s24, s24, 0x1000
	s_addc_u32 s25, s25, 0
	s_add_u32 s26, s26, 0x2800
	s_addc_u32 s27, s27, 0
	s_add_u32 s28, s28, 0x100
	s_addc_u32 s29, s29, 0
	global_load_dwordx4 v[158:161], v0, s[24:25] offset:-4096
	global_load_dwordx4 v[162:165], v0, s[24:25] offset:-3840
	global_load_dwordx4 v[166:169], v0, s[24:25] offset:-3584
	global_load_dwordx4 v[170:173], v0, s[24:25] offset:-3328
	global_load_dwordx4 v[174:177], v0, s[24:25] offset:-3072
	global_load_dwordx4 v[178:181], v0, s[24:25] offset:-2816
	global_load_dwordx4 v[182:185], v0, s[24:25] offset:-2560
	s_waitcnt lgkmcnt(0)
	s_barrier
	s_mov_b32 s38, 0
.Lsc_loop:
	global_load_dwordx2 v[24:25], v13, s[26:27]
	global_load_dwordx2 v[26:27], v13, s[26:27] offset:128
	global_load_dwordx2 v[28:29], v13, s[26:27] offset:256
	global_load_dwordx2 v[30:31], v13, s[26:27] offset:384
	global_load_ushort v32, v14, s[26:27]
	global_load_dwordx2 v[34:35], v15, s[28:29]
	ds_read_b128 v[44:47], v0 offset:256
	ds_read_b128 v[48:51], v0 offset:512
	ds_read_b128 v[56:59], v0 offset:1024
	ds_read_b128 v[52:55], v0 offset:768
	ds_read_b128 v[80:83], v1 offset:0
	ds_read_b128 v[64:67], v0 offset:1536
	ds_read_b128 v[68:71], v0 offset:1792
	ds_read_b128 v[76:79], v0 offset:2304
	ds_read_b128 v[72:75], v0 offset:2048
	s_waitcnt lgkmcnt(7)
	v_pk_mul_f32 v[88:89], v[4:5], v[44:45] op_sel_hi:[0,1]
	v_pk_mul_f32 v[90:91], v[6:7], v[48:49] op_sel_hi:[0,1]
	v_pk_fma_f32 v[88:89], v[4:5], v[46:47], v[88:89] op_sel:[1,0,0] op_sel_hi:[1,1,1]
	v_pk_fma_f32 v[90:91], v[6:7], v[50:51], v[90:91] op_sel:[1,0,0] op_sel_hi:[1,1,1]
	v_pk_add_f32 v[100:101], v[88:89], v[90:91]
	s_waitcnt lgkmcnt(4)
	v_pk_mul_f32 v[96:97], v[80:81], v[56:57] op_sel:[0,0] op_sel_hi:[0,1]
	v_pk_mul_f32 v[98:99], v[80:81], v[58:59] op_sel:[0,0] op_sel_hi:[0,1]
	v_add_f32_dpp v93, v100, v100 quad_perm:[1,0,3,2] row_mask:0xf bank_mask:0xf
	s_waitcnt vmcnt(12)
	v_pk_fma_f32 v[96:97], v[4:5], v[158:159], v[96:97]
	v_pk_fma_f32 v[98:99], v[6:7], v[160:161], v[98:99]
	v_add_f32_dpp v92, v93, v93 quad_perm:[2,3,0,1] row_mask:0xf bank_mask:0xf
	ds_read_b128 v[142:145], v0 offset:2816
	ds_read_b128 v[146:149], v0 offset:3072
	v_add_f32_dpp v93, v92, v92 row_ror:4 row_mask:0xf bank_mask:0xf
	ds_read_b128 v[154:157], v0 offset:3584
	ds_read_b128 v[150:153], v0 offset:3328
	v_add_f32_dpp v94, v93, v93 row_ror:8 row_mask:0xf bank_mask:0xf
	v_add_f32_dpp v108, v93, v93 row_ror:8 row_mask:0xf bank_mask:0x1
	v_pk_fma_f32 v[4:5], v[94:95], v[52:53], v[96:97] op_sel_hi:[0,1,1] neg_lo:[1,0,0] neg_hi:[1,0,0]
	v_pk_fma_f32 v[6:7], v[94:95], v[54:55], v[98:99] op_sel_hi:[0,1,1] neg_lo:[1,0,0] neg_hi:[1,0,0]
	global_load_dwordx4 v[186:189], v0, s[24:25] offset:-2304
	s_waitcnt lgkmcnt(6)
	v_pk_mul_f32 v[88:89], v[4:5], v[64:65] op_sel_hi:[0,1]
	v_pk_mul_f32 v[90:91], v[6:7], v[68:69] op_sel_hi:[0,1]
	v_pk_fma_f32 v[88:89], v[4:5], v[66:67], v[88:89] op_sel:[1,0,0] op_sel_hi:[1,1,1]
	v_pk_fma_f32 v[90:91], v[6:7], v[70:71], v[90:91] op_sel:[1,0,0] op_sel_hi:[1,1,1]
	v_pk_add_f32 v[102:103], v[88:89], v[90:91]
	s_waitcnt lgkmcnt(5)
	v_pk_mul_f32 v[96:97], v[80:81], v[76:77] op_sel:[1,0] op_sel_hi:[1,1]
	v_pk_mul_f32 v[98:99], v[80:81], v[78:79] op_sel:[1,0] op_sel_hi:[1,1]
	v_add_f32_dpp v93, v102, v102 quad_perm:[1,0,3,2] row_mask:0xf bank_mask:0xf
	s_waitcnt vmcnt(12)
	v_pk_fma_f32 v[96:97], v[4:5], v[162:163], v[96:97]
	v_pk_fma_f32 v[98:99], v[6:7], v[164:165], v[98:99]
	v_add_f32_dpp v92, v93, v93 quad_perm:[2,3,0,1] row_mask:0xf bank_mask:0xf
	ds_read_b128 v[44:47], v0 offset:4096
	ds_read_b128 v[48:51], v0 offset:4352
	v_add_f32_dpp v93, v92, v92 row_ror:4 row_mask:0xf bank_mask:0xf
	ds_read_b128 v[56:59], v0 offset:4864
	ds_read_b128 v[52:55], v0 offset:4608
	v_add_f32_dpp v94, v93, v93 row_ror:8 row_mask:0xf bank_mask:0xf
	v_add_f32_dpp v108, v93, v93 row_ror:8 row_mask:0xf bank_mask:0x4
	ds_read_b128 v[84:87], v1 offset:16
	s_waitcnt lgkmcnt(9)
	v_pk_fma_f32 v[4:5], v[94:95], v[72:73], v[96:97] op_sel_hi:[0,1,1] neg_lo:[1,0,0] neg_hi:[1,0,0]
	v_pk_fma_f32 v[6:7], v[94:95], v[74:75], v[98:99] op_sel_hi:[0,1,1] neg_lo:[1,0,0] neg_hi:[1,0,0]
	global_load_dwordx4 v[158:161], v0, s[24:25] offset:-2048
	v_add_f32_dpp v101, v101, v101 row_ror:8 row_mask:0xf bank_mask:0x3
	s_nop 1
	v_add_f32_dpp v101, v103, v103 row_ror:8 row_mask:0xf bank_mask:0xc
	s_waitcnt lgkmcnt(7)
; __device__ __forceinline__ void rwkv_scan2_item(const Params& p, int item, char* ldsraw) {
;     ...
;         for (int q = 0; q < 16; q++) {
;           const f32x4 cw = nw, ckk = nkk, ckka = nkka, ck = nk; const float cvA = nvA, cvB = nvB;
;           if (q < 15) R_LOAD(q + 1)
;           __builtin_amdgcn_sched_barrier(0);
;           float mA0 = mul_s(a0, ckk.x), mA1 = mul_s(a2, ckk.z), mB0 = mul_s(b0, ckk.x), mB1 = mul_s(b2, ckk.z);
;           mA0 = fma_s(a1, ckk.y, mA0); mA1 = fma_s(a3, ckk.w, mA1); mB0 = fma_s(b1, ckk.y, mB0); mB1 = fma_s(b3, ckk.w, mB1);
;           float psA = add_s(mA0, mA1), psB = add_s(mB0, mB1);
;           psA = row16_sum(psA); psB = row16_sum(psB);
;           { const float t0 = fnma_s(psA, ckka.x, mul_s(cvA, ck.x)), t1 = fnma_s(psA, ckka.y, mul_s(cvA, ck.y));
;             const float t2 = fnma_s(psA, ckka.z, mul_s(cvA, ck.z)), t3 = fnma_s(psA, ckka.w, mul_s(cvA, ck.w));
;             a0 = fma_s(a0, cw.x, t0); a1 = fma_s(a1, cw.y, t1); a2 = fma_s(a2, cw.z, t2); a3 = fma_s(a3, cw.w, t3); }
;           { const float t0 = fnma_s(psB, ckka.x, mul_s(cvB, ck.x)), t1 = fnma_s(psB, ckka.y, mul_s(cvB, ck.y));
;             const float t2 = fnma_s(psB, ckka.z, mul_s(cvB, ck.z)), t3 = fnma_s(psB, ckka.w, mul_s(cvB, ck.w));
;             b0 = fma_s(b0, cw.x, t0); b1 = fma_s(b1, cw.y, t1); b2 = fma_s(b2, cw.z, t2); b3 = fma_s(b3, cw.w, t3); }
;           sakA = sel_eq(sakA, psA, jl, q); sakB = sel_eq(sakB, psB, jl, q);
;     ...
;           float nA0 = mul_s(a0, cwr.x), nA1 = mul_s(a2, cwr.z), nB0 = mul_s(b0, cwr.x), nB1 = mul_s(b2, cwr.z);
;           nA0 = fma_s(a1, cwr.y, nA0); nA1 = fma_s(a3, cwr.w, nA1); nB0 = fma_s(b1, cwr.y, nB0); nB1 = fma_s(b3, cwr.w, nB1);
;           float puA = add_s(nA0, nA1), puB = add_s(nB0, nB1);
;           puA = row16_sum(puA); puB = row16_sum(puB);
;           { const float t0 = fnma_s(psA, ckka.x, mul_s(cvA, ck.x)), t1 = fnma_s(psA, ckka.y, mul_s(cvA, ck.y));
;             const float t2 = fnma_s(psA, ckka.z, mul_s(cvA, ck.z)), t3 = fnma_s(psA, ckka.w, mul_s(cvA, ck.w));
;             a0 = fma_s(a0, cw.x, t0); a1 = fma_s(a1, cw.y, t1); a2 = fma_s(a2, cw.z, t2); a3 = fma_s(a3, cw.w, t3); }
;           { const float t0 = fnma_s(psB, ckka.x, mul_s(cvB, ck.x)), t1 = fnma_s(psB, ckka.y, mul_s(cvB, ck.y));
;             const float t2 = fnma_s(psB, ckka.z, mul_s(cvB, ck.z)), t3 = fnma_s(psB, ckka.w, mul_s(cvB, ck.w));
	v_pk_mul_f32 v[88:89], v[4:5], v[142:143] op_sel_hi:[0,1]
	v_pk_mul_f32 v[90:91], v[6:7], v[146:147] op_sel_hi:[0,1]
	v_pk_fma_f32 v[88:89], v[4:5], v[144:145], v[88:89] op_sel:[1,0,0] op_sel_hi:[1,1,1]
	v_pk_fma_f32 v[90:91], v[6:7], v[148:149], v[90:91] op_sel:[1,0,0] op_sel_hi:[1,1,1]
	v_pk_add_f32 v[104:105], v[88:89], v[90:91]
	s_waitcnt lgkmcnt(6)
	v_pk_mul_f32 v[96:97], v[82:83], v[154:155] op_sel:[0,0] op_sel_hi:[0,1]
	v_pk_mul_f32 v[98:99], v[82:83], v[156:157] op_sel:[0,0] op_sel_hi:[0,1]
	v_add_f32_dpp v93, v104, v104 quad_perm:[1,0,3,2] row_mask:0xf bank_mask:0xf
	s_waitcnt vmcnt(12)
	v_pk_fma_f32 v[96:97], v[4:5], v[166:167], v[96:97]
	v_pk_fma_f32 v[98:99], v[6:7], v[168:169], v[98:99]
	v_add_f32_dpp v92, v93, v93 quad_perm:[2,3,0,1] row_mask:0xf bank_mask:0xf
	ds_read_b128 v[64:67], v0 offset:5376
	ds_read_b128 v[68:71], v0 offset:5632
	v_add_f32_dpp v93, v92, v92 row_ror:4 row_mask:0xf bank_mask:0xf
	ds_read_b128 v[76:79], v0 offset:6144
	ds_read_b128 v[72:75], v0 offset:5888
	v_add_f32_dpp v94, v93, v93 row_ror:8 row_mask:0xf bank_mask:0xf
	v_add_f32_dpp v108, v93, v93 row_ror:8 row_mask:0xf bank_mask:0x2
	s_waitcnt lgkmcnt(9)
	v_pk_fma_f32 v[4:5], v[94:95], v[150:151], v[96:97] op_sel_hi:[0,1,1] neg_lo:[1,0,0] neg_hi:[1,0,0]
	v_pk_fma_f32 v[6:7], v[94:95], v[152:153], v[98:99] op_sel_hi:[0,1,1] neg_lo:[1,0,0] neg_hi:[1,0,0]
	global_load_dwordx4 v[162:165], v0, s[24:25] offset:-1792
	s_waitcnt lgkmcnt(7)
	v_pk_mul_f32 v[88:89], v[4:5], v[44:45] op_sel_hi:[0,1]
	v_pk_mul_f32 v[90:91], v[6:7], v[48:49] op_sel_hi:[0,1]
	v_pk_fma_f32 v[88:89], v[4:5], v[46:47], v[88:89] op_sel:[1,0,0] op_sel_hi:[1,1,1]
	v_pk_fma_f32 v[90:91], v[6:7], v[50:51], v[90:91] op_sel:[1,0,0] op_sel_hi:[1,1,1]
	v_pk_add_f32 v[132:133], v[88:89], v[90:91]
	s_waitcnt lgkmcnt(6)
	v_pk_mul_f32 v[96:97], v[82:83], v[56:57] op_sel:[1,0] op_sel_hi:[1,1]
	v_pk_mul_f32 v[98:99], v[82:83], v[58:59] op_sel:[1,0] op_sel_hi:[1,1]
	v_add_f32_dpp v93, v132, v132 quad_perm:[1,0,3,2] row_mask:0xf bank_mask:0xf
	s_waitcnt vmcnt(12)
	v_pk_fma_f32 v[96:97], v[4:5], v[170:171], v[96:97]
	v_pk_fma_f32 v[98:99], v[6:7], v[172:173], v[98:99]
	v_add_f32_dpp v92, v93, v93 quad_perm:[2,3,0,1] row_mask:0xf bank_mask:0xf
	ds_read_b128 v[142:145], v0 offset:6656
	ds_read_b128 v[146:149], v0 offset:6912
	v_add_f32_dpp v93, v92, v92 row_ror:4 row_mask:0xf bank_mask:0xf
	ds_read_b128 v[154:157], v0 offset:7424
	ds_read_b128 v[150:153], v0 offset:7168
	v_add_f32_dpp v94, v93, v93 row_ror:8 row_mask:0xf bank_mask:0xf
	v_add_f32_dpp v108, v93, v93 row_ror:8 row_mask:0xf bank_mask:0x8
	s_waitcnt lgkmcnt(9)
	v_pk_fma_f32 v[4:5], v[94:95], v[52:53], v[96:97] op_sel_hi:[0,1,1] neg_lo:[1,0,0] neg_hi:[1,0,0]
	v_pk_fma_f32 v[6:7], v[94:95], v[54:55], v[98:99] op_sel_hi:[0,1,1] neg_lo:[1,0,0] neg_hi:[1,0,0]
	global_load_dwordx4 v[166:169], v0, s[24:25] offset:-1536
	v_add_f32_dpp v105, v105, v105 row_ror:8 row_mask:0xf bank_mask:0x3
	s_nop 1
	v_add_f32_dpp v105, v133, v133 row_ror:8 row_mask:0xf bank_mask:0xc
	v_add_f32_dpp v101, v101, v101 row_half_mirror row_mask:0xf bank_mask:0x5
	s_nop 1
	v_add_f32_dpp v101, v105, v105 row_half_mirror row_mask:0xf bank_mask:0xa
	s_waitcnt lgkmcnt(6)
	v_pk_mul_f32 v[88:89], v[4:5], v[64:65] op_sel_hi:[0,1]
	v_pk_mul_f32 v[90:91], v[6:7], v[68:69] op_sel_hi:[0,1]
	v_pk_fma_f32 v[88:89], v[4:5], v[66:67], v[88:89] op_sel:[1,0,0] op_sel_hi:[1,1,1]
	v_pk_fma_f32 v[90:91], v[6:7], v[70:71], v[90:91] op_sel:[1,0,0] op_sel_hi:[1,1,1]
	v_pk_add_f32 v[134:135], v[88:89], v[90:91]
	s_waitcnt lgkmcnt(5)
	v_pk_mul_f32 v[96:97], v[84:85], v[76:77] op_sel:[0,0] op_sel_hi:[0,1]
	v_pk_mul_f32 v[98:99], v[84:85], v[78:79] op_sel:[0,0] op_sel_hi:[0,1]
	v_add_f32_dpp v93, v134, v134 quad_perm:[1,0,3,2] row_mask:0xf bank_mask:0xf
	s_waitcnt vmcnt(12)
	v_pk_fma_f32 v[96:97], v[4:5], v[174:175], v[96:97]
	v_pk_fma_f32 v[98:99], v[6:7], v[176:177], v[98:99]
	v_add_f32_dpp v92, v93, v93 quad_perm:[2,3,0,1] row_mask:0xf bank_mask:0xf
	ds_read_b128 v[44:47], v0 offset:7936
	ds_read_b128 v[48:51], v0 offset:8192
	v_add_f32_dpp v93, v92, v92 row_ror:4 row_mask:0xf bank_mask:0xf
	ds_read_b128 v[56:59], v0 offset:8704
	ds_read_b128 v[52:55], v0 offset:8448
	v_add_f32_dpp v94, v93, v93 row_ror:8 row_mask:0xf bank_mask:0xf
	v_add_f32_dpp v109, v93, v93 row_ror:8 row_mask:0xf bank_mask:0x1
	s_waitcnt lgkmcnt(8)
	v_pk_fma_f32 v[4:5], v[94:95], v[72:73], v[96:97] op_sel_hi:[0,1,1] neg_lo:[1,0,0] neg_hi:[1,0,0]
	v_pk_fma_f32 v[6:7], v[94:95], v[74:75], v[98:99] op_sel_hi:[0,1,1] neg_lo:[1,0,0] neg_hi:[1,0,0]
	global_load_dwordx4 v[170:173], v0, s[24:25] offset:-1280
	s_waitcnt lgkmcnt(6)
	v_pk_mul_f32 v[88:89], v[4:5], v[142:143] op_sel_hi:[0,1]
	v_pk_mul_f32 v[90:91], v[6:7], v[146:147] op_sel_hi:[0,1]
	v_pk_fma_f32 v[88:89], v[4:5], v[144:145], v[88:89] op_sel:[1,0,0] op_sel_hi:[1,1,1]
	v_pk_fma_f32 v[90:91], v[6:7], v[148:149], v[90:91] op_sel:[1,0,0] op_sel_hi:[1,1,1]
	v_pk_add_f32 v[136:137], v[88:89], v[90:91]
	s_waitcnt lgkmcnt(5)
	v_pk_mul_f32 v[96:97], v[84:85], v[154:155] op_sel:[1,0] op_sel_hi:[1,1]
	v_pk_mul_f32 v[98:99], v[84:85], v[156:157] op_sel:[1,0] op_sel_hi:[1,1]
	v_add_f32_dpp v93, v136, v136 quad_perm:[1,0,3,2] row_mask:0xf bank_mask:0xf
	s_waitcnt vmcnt(12)
	v_pk_fma_f32 v[96:97], v[4:5], v[178:179], v[96:97]
	v_pk_fma_f32 v[98:99], v[6:7], v[180:181], v[98:99]
	v_add_f32_dpp v92, v93, v93 quad_perm:[2,3,0,1] row_mask:0xf bank_mask:0xf
	ds_read_b128 v[64:67], v0 offset:9216
	ds_read_b128 v[68:71], v0 offset:9472
	v_add_f32_dpp v93, v92, v92 row_ror:4 row_mask:0xf bank_mask:0xf
	ds_read_b128 v[76:79], v0 offset:9984
	ds_read_b128 v[72:75], v0 offset:9728
	v_add_f32_dpp v94, v93, v93 row_ror:8 row_mask:0xf bank_mask:0xf
	v_add_f32_dpp v109, v93, v93 row_ror:8 row_mask:0xf bank_mask:0x4
	ds_read_b128 v[80:83], v1 offset:32
	s_waitcnt lgkmcnt(9)
; __device__ __forceinline__ void rwkv_scan2_item(const Params& p, int item, char* ldsraw) {
;     ...
;         for (int q = 0; q < 16; q++) {
;           const f32x4 cw = nw, ckk = nkk, ckka = nkka, ck = nk; const float cvA = nvA, cvB = nvB;
;           if (q < 15) R_LOAD(q + 1)
;           __builtin_amdgcn_sched_barrier(0);
;           float mA0 = mul_s(a0, ckk.x), mA1 = mul_s(a2, ckk.z), mB0 = mul_s(b0, ckk.x), mB1 = mul_s(b2, ckk.z);
;           mA0 = fma_s(a1, ckk.y, mA0); mA1 = fma_s(a3, ckk.w, mA1); mB0 = fma_s(b1, ckk.y, mB0); mB1 = fma_s(b3, ckk.w, mB1);
;           float psA = add_s(mA0, mA1), psB = add_s(mB0, mB1);
;           psA = row16_sum(psA); psB = row16_sum(psB);
;           { const float t0 = fnma_s(psA, ckka.x, mul_s(cvA, ck.x)), t1 = fnma_s(psA, ckka.y, mul_s(cvA, ck.y));
;             const float t2 = fnma_s(psA, ckka.z, mul_s(cvA, ck.z)), t3 = fnma_s(psA, ckka.w, mul_s(cvA, ck.w));
;             a0 = fma_s(a0, cw.x, t0); a1 = fma_s(a1, cw.y, t1); a2 = fma_s(a2, cw.z, t2); a3 = fma_s(a3, cw.w, t3); }
;           { const float t0 = fnma_s(psB, ckka.x, mul_s(cvB, ck.x)), t1 = fnma_s(psB, ckka.y, mul_s(cvB, ck.y));
;             const float t2 = fnma_s(psB, ckka.z, mul_s(cvB, ck.z)), t3 = fnma_s(psB, ckka.w, mul_s(cvB, ck.w));
;             b0 = fma_s(b0, cw.x, t0); b1 = fma_s(b1, cw.y, t1); b2 = fma_s(b2, cw.z, t2); b3 = fma_s(b3, cw.w, t3); }
;           sakA = sel_eq(sakA, psA, jl, q); sakB = sel_eq(sakB, psB, jl, q);
;     ...
;           float nA0 = mul_s(a0, cwr.x), nA1 = mul_s(a2, cwr.z), nB0 = mul_s(b0, cwr.x), nB1 = mul_s(b2, cwr.z);
;           nA0 = fma_s(a1, cwr.y, nA0); nA1 = fma_s(a3, cwr.w, nA1); nB0 = fma_s(b1, cwr.y, nB0); nB1 = fma_s(b3, cwr.w, nB1);
;           float puA = add_s(nA0, nA1), puB = add_s(nB0, nB1);
;           puA = row16_sum(puA); puB = row16_sum(puB);
;           { const float t0 = fnma_s(psA, ckka.x, mul_s(cvA, ck.x)), t1 = fnma_s(psA, ckka.y, mul_s(cvA, ck.y));
;             const float t2 = fnma_s(psA, ckka.z, mul_s(cvA, ck.z)), t3 = fnma_s(psA, ckka.w, mul_s(cvA, ck.w));
;             a0 = fma_s(a0, cw.x, t0); a1 = fma_s(a1, cw.y, t1); a2 = fma_s(a2, cw.z, t2); a3 = fma_s(a3, cw.w, t3); }
;           { const float t0 = fnma_s(psB, ckka.x, mul_s(cvB, ck.x)), t1 = fnma_s(psB, ckka.y, mul_s(cvB, ck.y));
;             const float t2 = fnma_s(psB, ckka.z, mul_s(cvB, ck.z)), t3 = fnma_s(psB, ckka.w, mul_s(cvB, ck.w));
	v_pk_fma_f32 v[4:5], v[94:95], v[150:151], v[96:97] op_sel_hi:[0,1,1] neg_lo:[1,0,0] neg_hi:[1,0,0]
	v_pk_fma_f32 v[6:7], v[94:95], v[152:153], v[98:99] op_sel_hi:[0,1,1] neg_lo:[1,0,0] neg_hi:[1,0,0]
	global_load_dwordx4 v[174:177], v0, s[24:25] offset:-1024
	v_add_f32_dpp v135, v135, v135 row_ror:8 row_mask:0xf bank_mask:0x3
	s_nop 1
	v_add_f32_dpp v135, v137, v137 row_ror:8 row_mask:0xf bank_mask:0xc
	s_waitcnt lgkmcnt(7)
	v_pk_mul_f32 v[88:89], v[4:5], v[44:45] op_sel_hi:[0,1]
	v_pk_mul_f32 v[90:91], v[6:7], v[48:49] op_sel_hi:[0,1]
	v_pk_fma_f32 v[88:89], v[4:5], v[46:47], v[88:89] op_sel:[1,0,0] op_sel_hi:[1,1,1]
	v_pk_fma_f32 v[90:91], v[6:7], v[50:51], v[90:91] op_sel:[1,0,0] op_sel_hi:[1,1,1]
	v_pk_add_f32 v[102:103], v[88:89], v[90:91]
	s_waitcnt lgkmcnt(6)
	v_pk_mul_f32 v[96:97], v[86:87], v[56:57] op_sel:[0,0] op_sel_hi:[0,1]
	v_pk_mul_f32 v[98:99], v[86:87], v[58:59] op_sel:[0,0] op_sel_hi:[0,1]
	v_add_f32_dpp v93, v102, v102 quad_perm:[1,0,3,2] row_mask:0xf bank_mask:0xf
	s_waitcnt vmcnt(12)
	v_pk_fma_f32 v[96:97], v[4:5], v[182:183], v[96:97]
	v_pk_fma_f32 v[98:99], v[6:7], v[184:185], v[98:99]
	v_add_f32_dpp v92, v93, v93 quad_perm:[2,3,0,1] row_mask:0xf bank_mask:0xf
	ds_read_b128 v[142:145], v0 offset:10496
	ds_read_b128 v[146:149], v0 offset:10752
	v_add_f32_dpp v93, v92, v92 row_ror:4 row_mask:0xf bank_mask:0xf
	ds_read_b128 v[154:157], v0 offset:11264
	ds_read_b128 v[150:153], v0 offset:11008
	v_add_f32_dpp v94, v93, v93 row_ror:8 row_mask:0xf bank_mask:0xf
	v_add_f32_dpp v109, v93, v93 row_ror:8 row_mask:0xf bank_mask:0x2
	s_waitcnt lgkmcnt(9)
	v_pk_fma_f32 v[4:5], v[94:95], v[52:53], v[96:97] op_sel_hi:[0,1,1] neg_lo:[1,0,0] neg_hi:[1,0,0]
	v_pk_fma_f32 v[6:7], v[94:95], v[54:55], v[98:99] op_sel_hi:[0,1,1] neg_lo:[1,0,0] neg_hi:[1,0,0]
	global_load_dwordx4 v[178:181], v0, s[24:25] offset:-768
	s_waitcnt lgkmcnt(7)
	v_pk_mul_f32 v[88:89], v[4:5], v[64:65] op_sel_hi:[0,1]
	v_pk_mul_f32 v[90:91], v[6:7], v[68:69] op_sel_hi:[0,1]
	v_pk_fma_f32 v[88:89], v[4:5], v[66:67], v[88:89] op_sel:[1,0,0] op_sel_hi:[1,1,1]
	v_pk_fma_f32 v[90:91], v[6:7], v[70:71], v[90:91] op_sel:[1,0,0] op_sel_hi:[1,1,1]
	v_pk_add_f32 v[132:133], v[88:89], v[90:91]
	s_waitcnt lgkmcnt(6)
	v_pk_mul_f32 v[96:97], v[86:87], v[76:77] op_sel:[1,0] op_sel_hi:[1,1]
	v_pk_mul_f32 v[98:99], v[86:87], v[78:79] op_sel:[1,0] op_sel_hi:[1,1]
	v_add_f32_dpp v93, v132, v132 quad_perm:[1,0,3,2] row_mask:0xf bank_mask:0xf
	s_waitcnt vmcnt(6)
	v_pk_fma_f32 v[96:97], v[4:5], v[186:187], v[96:97]
	v_pk_fma_f32 v[98:99], v[6:7], v[188:189], v[98:99]
	v_add_f32_dpp v92, v93, v93 quad_perm:[2,3,0,1] row_mask:0xf bank_mask:0xf
	ds_read_b128 v[44:47], v0 offset:11776
	ds_read_b128 v[48:51], v0 offset:12032
	v_add_f32_dpp v93, v92, v92 row_ror:4 row_mask:0xf bank_mask:0xf
	ds_read_b128 v[56:59], v0 offset:12544
	ds_read_b128 v[52:55], v0 offset:12288
	v_add_f32_dpp v94, v93, v93 row_ror:8 row_mask:0xf bank_mask:0xf
	v_add_f32_dpp v109, v93, v93 row_ror:8 row_mask:0xf bank_mask:0x8
	s_waitcnt lgkmcnt(9)
	v_pk_fma_f32 v[4:5], v[94:95], v[72:73], v[96:97] op_sel_hi:[0,1,1] neg_lo:[1,0,0] neg_hi:[1,0,0]
	v_pk_fma_f32 v[6:7], v[94:95], v[74:75], v[98:99] op_sel_hi:[0,1,1] neg_lo:[1,0,0] neg_hi:[1,0,0]
	global_load_dwordx4 v[182:185], v0, s[24:25] offset:-512
	v_add_f32_dpp v103, v103, v103 row_ror:8 row_mask:0xf bank_mask:0x3
	s_nop 1
	v_add_f32_dpp v103, v133, v133 row_ror:8 row_mask:0xf bank_mask:0xc
	v_add_f32_dpp v135, v135, v135 row_half_mirror row_mask:0xf bank_mask:0x5
	s_nop 1
	v_add_f32_dpp v135, v103, v103 row_half_mirror row_mask:0xf bank_mask:0xa
	v_cndmask_b32_e64 v106, v135, v101, s[36:37]
	v_cndmask_b32_e64 v107, v101, v135, s[36:37]
	s_nop 1
	v_add_f32_dpp v101, v106, v107 quad_perm:[2,3,0,1] row_mask:0xf bank_mask:0xf
	s_waitcnt lgkmcnt(6)
	v_pk_mul_f32 v[88:89], v[4:5], v[142:143] op_sel_hi:[0,1]
	v_pk_mul_f32 v[90:91], v[6:7], v[146:147] op_sel_hi:[0,1]
	v_pk_fma_f32 v[88:89], v[4:5], v[144:145], v[88:89] op_sel:[1,0,0] op_sel_hi:[1,1,1]
	v_pk_fma_f32 v[90:91], v[6:7], v[148:149], v[90:91] op_sel:[1,0,0] op_sel_hi:[1,1,1]
	v_pk_add_f32 v[104:105], v[88:89], v[90:91]
	s_waitcnt lgkmcnt(5)
	v_pk_mul_f32 v[96:97], v[80:81], v[154:155] op_sel:[0,0] op_sel_hi:[0,1]
	v_pk_mul_f32 v[98:99], v[80:81], v[156:157] op_sel:[0,0] op_sel_hi:[0,1]
	v_add_f32_dpp v93, v104, v104 quad_perm:[1,0,3,2] row_mask:0xf bank_mask:0xf
	s_waitcnt vmcnt(6)
	v_pk_fma_f32 v[96:97], v[4:5], v[158:159], v[96:97]
	v_pk_fma_f32 v[98:99], v[6:7], v[160:161], v[98:99]
	v_add_f32_dpp v92, v93, v93 quad_perm:[2,3,0,1] row_mask:0xf bank_mask:0xf
	ds_read_b128 v[64:67], v0 offset:13056
	ds_read_b128 v[68:71], v0 offset:13312
	v_add_f32_dpp v93, v92, v92 row_ror:4 row_mask:0xf bank_mask:0xf
	ds_read_b128 v[76:79], v0 offset:13824
	ds_read_b128 v[72:75], v0 offset:13568
	v_add_f32_dpp v94, v93, v93 row_ror:8 row_mask:0xf bank_mask:0xf
	v_add_f32_dpp v110, v93, v93 row_ror:8 row_mask:0xf bank_mask:0x1
	s_waitcnt lgkmcnt(8)
	v_pk_fma_f32 v[4:5], v[94:95], v[150:151], v[96:97] op_sel_hi:[0,1,1] neg_lo:[1,0,0] neg_hi:[1,0,0]
	v_pk_fma_f32 v[6:7], v[94:95], v[152:153], v[98:99] op_sel_hi:[0,1,1] neg_lo:[1,0,0] neg_hi:[1,0,0]
	global_load_dwordx4 v[186:189], v0, s[24:25] offset:-256
	s_waitcnt lgkmcnt(6)
	v_pk_mul_f32 v[88:89], v[4:5], v[44:45] op_sel_hi:[0,1]
	v_pk_mul_f32 v[90:91], v[6:7], v[48:49] op_sel_hi:[0,1]
	v_pk_fma_f32 v[88:89], v[4:5], v[46:47], v[88:89] op_sel:[1,0,0] op_sel_hi:[1,1,1]
	v_pk_fma_f32 v[90:91], v[6:7], v[50:51], v[90:91] op_sel:[1,0,0] op_sel_hi:[1,1,1]
	v_pk_add_f32 v[136:137], v[88:89], v[90:91]
	s_waitcnt lgkmcnt(5)
; __device__ __forceinline__ void rwkv_scan2_item(const Params& p, int item, char* ldsraw) {
;     ...
;         for (int q = 0; q < 16; q++) {
;           const f32x4 cw = nw, ckk = nkk, ckka = nkka, ck = nk; const float cvA = nvA, cvB = nvB;
;           if (q < 15) R_LOAD(q + 1)
;           __builtin_amdgcn_sched_barrier(0);
;           float mA0 = mul_s(a0, ckk.x), mA1 = mul_s(a2, ckk.z), mB0 = mul_s(b0, ckk.x), mB1 = mul_s(b2, ckk.z);
;           mA0 = fma_s(a1, ckk.y, mA0); mA1 = fma_s(a3, ckk.w, mA1); mB0 = fma_s(b1, ckk.y, mB0); mB1 = fma_s(b3, ckk.w, mB1);
;           float psA = add_s(mA0, mA1), psB = add_s(mB0, mB1);
;           psA = row16_sum(psA); psB = row16_sum(psB);
;           { const float t0 = fnma_s(psA, ckka.x, mul_s(cvA, ck.x)), t1 = fnma_s(psA, ckka.y, mul_s(cvA, ck.y));
;             const float t2 = fnma_s(psA, ckka.z, mul_s(cvA, ck.z)), t3 = fnma_s(psA, ckka.w, mul_s(cvA, ck.w));
;             a0 = fma_s(a0, cw.x, t0); a1 = fma_s(a1, cw.y, t1); a2 = fma_s(a2, cw.z, t2); a3 = fma_s(a3, cw.w, t3); }
;           { const float t0 = fnma_s(psB, ckka.x, mul_s(cvB, ck.x)), t1 = fnma_s(psB, ckka.y, mul_s(cvB, ck.y));
;             const float t2 = fnma_s(psB, ckka.z, mul_s(cvB, ck.z)), t3 = fnma_s(psB, ckka.w, mul_s(cvB, ck.w));
;             b0 = fma_s(b0, cw.x, t0); b1 = fma_s(b1, cw.y, t1); b2 = fma_s(b2, cw.z, t2); b3 = fma_s(b3, cw.w, t3); }
;           sakA = sel_eq(sakA, psA, jl, q); sakB = sel_eq(sakB, psB, jl, q);
;     ...
;           float nA0 = mul_s(a0, cwr.x), nA1 = mul_s(a2, cwr.z), nB0 = mul_s(b0, cwr.x), nB1 = mul_s(b2, cwr.z);
;           nA0 = fma_s(a1, cwr.y, nA0); nA1 = fma_s(a3, cwr.w, nA1); nB0 = fma_s(b1, cwr.y, nB0); nB1 = fma_s(b3, cwr.w, nB1);
;           float puA = add_s(nA0, nA1), puB = add_s(nB0, nB1);
;           puA = row16_sum(puA); puB = row16_sum(puB);
;           { const float t0 = fnma_s(psA, ckka.x, mul_s(cvA, ck.x)), t1 = fnma_s(psA, ckka.y, mul_s(cvA, ck.y));
;             const float t2 = fnma_s(psA, ckka.z, mul_s(cvA, ck.z)), t3 = fnma_s(psA, ckka.w, mul_s(cvA, ck.w));
;             a0 = fma_s(a0, cw.x, t0); a1 = fma_s(a1, cw.y, t1); a2 = fma_s(a2, cw.z, t2); a3 = fma_s(a3, cw.w, t3); }
;           { const float t0 = fnma_s(psB, ckka.x, mul_s(cvB, ck.x)), t1 = fnma_s(psB, ckka.y, mul_s(cvB, ck.y));
;             const float t2 = fnma_s(psB, ckka.z, mul_s(cvB, ck.z)), t3 = fnma_s(psB, ckka.w, mul_s(cvB, ck.w));
	v_pk_mul_f32 v[96:97], v[80:81], v[56:57] op_sel:[1,0] op_sel_hi:[1,1]
	v_pk_mul_f32 v[98:99], v[80:81], v[58:59] op_sel:[1,0] op_sel_hi:[1,1]
	v_add_f32_dpp v93, v136, v136 quad_perm:[1,0,3,2] row_mask:0xf bank_mask:0xf
	s_waitcnt vmcnt(6)
	v_pk_fma_f32 v[96:97], v[4:5], v[162:163], v[96:97]
	v_pk_fma_f32 v[98:99], v[6:7], v[164:165], v[98:99]
	v_add_f32_dpp v92, v93, v93 quad_perm:[2,3,0,1] row_mask:0xf bank_mask:0xf
	ds_read_b128 v[142:145], v0 offset:14336
	ds_read_b128 v[146:149], v0 offset:14592
	v_add_f32_dpp v93, v92, v92 row_ror:4 row_mask:0xf bank_mask:0xf
	ds_read_b128 v[154:157], v0 offset:15104
	ds_read_b128 v[150:153], v0 offset:14848
	v_add_f32_dpp v94, v93, v93 row_ror:8 row_mask:0xf bank_mask:0xf
	v_add_f32_dpp v110, v93, v93 row_ror:8 row_mask:0xf bank_mask:0x4
	ds_read_b128 v[84:87], v1 offset:48
	s_waitcnt lgkmcnt(9)
	v_pk_fma_f32 v[4:5], v[94:95], v[52:53], v[96:97] op_sel_hi:[0,1,1] neg_lo:[1,0,0] neg_hi:[1,0,0]
	v_pk_fma_f32 v[6:7], v[94:95], v[54:55], v[98:99] op_sel_hi:[0,1,1] neg_lo:[1,0,0] neg_hi:[1,0,0]
	global_load_dwordx4 v[158:161], v0, s[24:25] offset:0
	v_add_f32_dpp v105, v105, v105 row_ror:8 row_mask:0xf bank_mask:0x3
	s_nop 1
	v_add_f32_dpp v105, v137, v137 row_ror:8 row_mask:0xf bank_mask:0xc
	s_waitcnt lgkmcnt(7)
	v_pk_mul_f32 v[88:89], v[4:5], v[64:65] op_sel_hi:[0,1]
	v_pk_mul_f32 v[90:91], v[6:7], v[68:69] op_sel_hi:[0,1]
	v_pk_fma_f32 v[88:89], v[4:5], v[66:67], v[88:89] op_sel:[1,0,0] op_sel_hi:[1,1,1]
	v_pk_fma_f32 v[90:91], v[6:7], v[70:71], v[90:91] op_sel:[1,0,0] op_sel_hi:[1,1,1]
	v_pk_add_f32 v[132:133], v[88:89], v[90:91]
	s_waitcnt lgkmcnt(6)
	v_pk_mul_f32 v[96:97], v[82:83], v[76:77] op_sel:[0,0] op_sel_hi:[0,1]
	v_pk_mul_f32 v[98:99], v[82:83], v[78:79] op_sel:[0,0] op_sel_hi:[0,1]
	v_add_f32_dpp v93, v132, v132 quad_perm:[1,0,3,2] row_mask:0xf bank_mask:0xf
	s_waitcnt vmcnt(6)
	v_pk_fma_f32 v[96:97], v[4:5], v[166:167], v[96:97]
	v_pk_fma_f32 v[98:99], v[6:7], v[168:169], v[98:99]
	v_add_f32_dpp v92, v93, v93 quad_perm:[2,3,0,1] row_mask:0xf bank_mask:0xf
	ds_read_b128 v[44:47], v0 offset:15616
	ds_read_b128 v[48:51], v0 offset:15872
	v_add_f32_dpp v93, v92, v92 row_ror:4 row_mask:0xf bank_mask:0xf
	ds_read_b128 v[56:59], v0 offset:16384
	ds_read_b128 v[52:55], v0 offset:16128
	v_add_f32_dpp v94, v93, v93 row_ror:8 row_mask:0xf bank_mask:0xf
	v_add_f32_dpp v110, v93, v93 row_ror:8 row_mask:0xf bank_mask:0x2
	s_waitcnt lgkmcnt(9)
	v_pk_fma_f32 v[4:5], v[94:95], v[72:73], v[96:97] op_sel_hi:[0,1,1] neg_lo:[1,0,0] neg_hi:[1,0,0]
	v_pk_fma_f32 v[6:7], v[94:95], v[74:75], v[98:99] op_sel_hi:[0,1,1] neg_lo:[1,0,0] neg_hi:[1,0,0]
	global_load_dwordx4 v[162:165], v0, s[24:25] offset:256
	s_waitcnt lgkmcnt(7)
	v_pk_mul_f32 v[88:89], v[4:5], v[142:143] op_sel_hi:[0,1]
	v_pk_mul_f32 v[90:91], v[6:7], v[146:147] op_sel_hi:[0,1]
	v_pk_fma_f32 v[88:89], v[4:5], v[144:145], v[88:89] op_sel:[1,0,0] op_sel_hi:[1,1,1]
	v_pk_fma_f32 v[90:91], v[6:7], v[148:149], v[90:91] op_sel:[1,0,0] op_sel_hi:[1,1,1]
	v_pk_add_f32 v[102:103], v[88:89], v[90:91]
	s_waitcnt lgkmcnt(6)
	v_pk_mul_f32 v[96:97], v[82:83], v[154:155] op_sel:[1,0] op_sel_hi:[1,1]
	v_pk_mul_f32 v[98:99], v[82:83], v[156:157] op_sel:[1,0] op_sel_hi:[1,1]
	v_add_f32_dpp v93, v102, v102 quad_perm:[1,0,3,2] row_mask:0xf bank_mask:0xf
	s_waitcnt vmcnt(6)
	v_pk_fma_f32 v[96:97], v[4:5], v[170:171], v[96:97]
	v_pk_fma_f32 v[98:99], v[6:7], v[172:173], v[98:99]
	v_add_f32_dpp v92, v93, v93 quad_perm:[2,3,0,1] row_mask:0xf bank_mask:0xf
	ds_read_b128 v[64:67], v0 offset:16896
	ds_read_b128 v[68:71], v0 offset:17152
	v_add_f32_dpp v93, v92, v92 row_ror:4 row_mask:0xf bank_mask:0xf
	ds_read_b128 v[76:79], v0 offset:17664
	ds_read_b128 v[72:75], v0 offset:17408
	v_add_f32_dpp v94, v93, v93 row_ror:8 row_mask:0xf bank_mask:0xf
	v_add_f32_dpp v110, v93, v93 row_ror:8 row_mask:0xf bank_mask:0x8
	s_waitcnt lgkmcnt(9)
	v_pk_fma_f32 v[4:5], v[94:95], v[150:151], v[96:97] op_sel_hi:[0,1,1] neg_lo:[1,0,0] neg_hi:[1,0,0]
	v_pk_fma_f32 v[6:7], v[94:95], v[152:153], v[98:99] op_sel_hi:[0,1,1] neg_lo:[1,0,0] neg_hi:[1,0,0]
	global_load_dwordx4 v[166:169], v0, s[24:25] offset:512
	v_add_f32_dpp v133, v133, v133 row_ror:8 row_mask:0xf bank_mask:0x3
	s_nop 1
	v_add_f32_dpp v133, v103, v103 row_ror:8 row_mask:0xf bank_mask:0xc
	v_add_f32_dpp v105, v105, v105 row_half_mirror row_mask:0xf bank_mask:0x5
	s_nop 1
	v_add_f32_dpp v105, v133, v133 row_half_mirror row_mask:0xf bank_mask:0xa
	s_waitcnt lgkmcnt(6)
	v_pk_mul_f32 v[88:89], v[4:5], v[44:45] op_sel_hi:[0,1]
	v_pk_mul_f32 v[90:91], v[6:7], v[48:49] op_sel_hi:[0,1]
	v_pk_fma_f32 v[88:89], v[4:5], v[46:47], v[88:89] op_sel:[1,0,0] op_sel_hi:[1,1,1]
	v_pk_fma_f32 v[90:91], v[6:7], v[50:51], v[90:91] op_sel:[1,0,0] op_sel_hi:[1,1,1]
	v_pk_add_f32 v[134:135], v[88:89], v[90:91]
	s_waitcnt lgkmcnt(5)
	v_pk_mul_f32 v[96:97], v[84:85], v[56:57] op_sel:[0,0] op_sel_hi:[0,1]
	v_pk_mul_f32 v[98:99], v[84:85], v[58:59] op_sel:[0,0] op_sel_hi:[0,1]
	v_add_f32_dpp v93, v134, v134 quad_perm:[1,0,3,2] row_mask:0xf bank_mask:0xf
	s_waitcnt vmcnt(6)
	v_pk_fma_f32 v[96:97], v[4:5], v[174:175], v[96:97]
	v_pk_fma_f32 v[98:99], v[6:7], v[176:177], v[98:99]
	v_add_f32_dpp v92, v93, v93 quad_perm:[2,3,0,1] row_mask:0xf bank_mask:0xf
	ds_read_b128 v[142:145], v0 offset:18176
	ds_read_b128 v[146:149], v0 offset:18432
	v_add_f32_dpp v93, v92, v92 row_ror:4 row_mask:0xf bank_mask:0xf
	ds_read_b128 v[154:157], v0 offset:18944
	ds_read_b128 v[150:153], v0 offset:18688
	v_add_f32_dpp v94, v93, v93 row_ror:8 row_mask:0xf bank_mask:0xf
	v_add_f32_dpp v111, v93, v93 row_ror:8 row_mask:0xf bank_mask:0x1
	s_waitcnt lgkmcnt(8)
; __device__ __forceinline__ float bf2f(unsigned short b) { return __uint_as_float(((unsigned)b) << 16); }
; __device__ __forceinline__ unsigned short f2bf(float f) { unsigned r; asm("v_cvt_pk_bf16_f32 %0, %1, %1" : "=v"(r) : "v"(f)); return (unsigned short)(r & 0xffffu); }
; __device__ __forceinline__ float bflo(unsigned u) { return __uint_as_float(u << 16); }
; __device__ __forceinline__ float bfhi(unsigned u) { return __uint_as_float(u & 0xffff0000u); }
; __device__ __forceinline__ float fma_s(float a, float b, float c) { float d; asm("v_fma_f32 %0, %1, %2, %3" : "=v"(d) : "v"(a), "v"(b), "v"(c)); return d; }
; __device__ __forceinline__ float fnma_s(float a, float b, float c) { float d; asm("v_fma_f32 %0, -%1, %2, %3" : "=v"(d) : "v"(a), "v"(b), "v"(c)); return d; }
; __device__ __forceinline__ float sel_eq(float keep, float v, int a, int b) { asm("v_cmp_eq_u32 vcc, %1, %2\n\tv_cndmask_b32 %0, %0, %3, vcc" : "+v"(keep) : "v"(a), "v"(b), "v"(v) : "vcc"); return keep; }
; __device__ __forceinline__ void rwkv_scan2_item(const Params& p, int item, char* ldsraw) {
;     ...
;   auto store = [&](int bi) {
;     float* d = buf + bi * CH + st * STEP;
;     *(f32x4*)(d + part * 4) = pw;
;     *(f32x4*)(d + 64 + part * 4) = (f32x4){bflo(pkk[0]), bfhi(pkk[0]), bflo(pkk[1]), bfhi(pkk[1])};
;     *(f32x4*)(d + 128 + part * 4) = (f32x4){bflo(pkka[0]), bfhi(pkka[0]), bflo(pkka[1]), bfhi(pkka[1])};
;     *(f32x4*)(d + 192 + part * 4) = (f32x4){bflo(pk[0]), bfhi(pk[0]), bflo(pk[1]), bfhi(pk[1])};
;     *(f32x4*)(d + 256 + part * 4) = (f32x4){bflo(pwr[0]), bfhi(pwr[0]), bflo(pwr[1]), bfhi(pwr[1])};
;     d[320 + part] = ident ? 0.f : bf2f(pv);
;     if (part < 2) d[336 + part] = pc;
;   };
;     ...
;           const float yA = fnma_s(psA, ccc.x, fma_s(cvA, ccc.y, puA)), yB = fnma_s(psB, ccc.x, fma_s(cvB, ccc.y, puB));
;           ykA = sel_eq(ykA, yA, jl, q); ykB = sel_eq(ykB, yB, jl, q);
;         }
;     ...
;         yout[(size_t)(c - 1) * ystride] = f2bf(ykA); yout[(size_t)(c - 1) * ystride + 8] = f2bf(ykB);
;       }
;     }
;     if (c + 1 < 128) store(bnext);
;     bi = bnext;
;     asm volatile("s_waitcnt lgkmcnt(0)" ::: "memory"); __builtin_amdgcn_s_barrier(); asm volatile("" ::: "memory");
	v_pk_fma_f32 v[4:5], v[94:95], v[52:53], v[96:97] op_sel_hi:[0,1,1] neg_lo:[1,0,0] neg_hi:[1,0,0]
	v_pk_fma_f32 v[6:7], v[94:95], v[54:55], v[98:99] op_sel_hi:[0,1,1] neg_lo:[1,0,0] neg_hi:[1,0,0]
	global_load_dwordx4 v[170:173], v0, s[24:25] offset:768
	s_waitcnt lgkmcnt(6)
	v_pk_mul_f32 v[88:89], v[4:5], v[64:65] op_sel_hi:[0,1]
	v_pk_mul_f32 v[90:91], v[6:7], v[68:69] op_sel_hi:[0,1]
	v_pk_fma_f32 v[88:89], v[4:5], v[66:67], v[88:89] op_sel:[1,0,0] op_sel_hi:[1,1,1]
	v_pk_fma_f32 v[90:91], v[6:7], v[70:71], v[90:91] op_sel:[1,0,0] op_sel_hi:[1,1,1]
	v_pk_add_f32 v[136:137], v[88:89], v[90:91]
	s_waitcnt lgkmcnt(5)
	v_pk_mul_f32 v[96:97], v[84:85], v[76:77] op_sel:[1,0] op_sel_hi:[1,1]
	v_pk_mul_f32 v[98:99], v[84:85], v[78:79] op_sel:[1,0] op_sel_hi:[1,1]
	v_add_f32_dpp v93, v136, v136 quad_perm:[1,0,3,2] row_mask:0xf bank_mask:0xf
	s_waitcnt vmcnt(6)
	v_pk_fma_f32 v[96:97], v[4:5], v[178:179], v[96:97]
	v_pk_fma_f32 v[98:99], v[6:7], v[180:181], v[98:99]
	v_add_f32_dpp v92, v93, v93 quad_perm:[2,3,0,1] row_mask:0xf bank_mask:0xf
	ds_read_b128 v[44:47], v0 offset:19456
	ds_read_b128 v[48:51], v0 offset:19712
	v_add_f32_dpp v93, v92, v92 row_ror:4 row_mask:0xf bank_mask:0xf
	ds_read_b128 v[56:59], v0 offset:20224
	ds_read_b128 v[52:55], v0 offset:19968
	v_add_f32_dpp v94, v93, v93 row_ror:8 row_mask:0xf bank_mask:0xf
	v_add_f32_dpp v111, v93, v93 row_ror:8 row_mask:0xf bank_mask:0x4
	ds_read_b32 v112, v10 offset:0
	s_waitcnt lgkmcnt(9)
	v_pk_fma_f32 v[4:5], v[94:95], v[72:73], v[96:97] op_sel_hi:[0,1,1] neg_lo:[1,0,0] neg_hi:[1,0,0]
	v_pk_fma_f32 v[6:7], v[94:95], v[74:75], v[98:99] op_sel_hi:[0,1,1] neg_lo:[1,0,0] neg_hi:[1,0,0]
	ds_read_b64 v[114:115], v11 offset:0
	global_load_dwordx4 v[174:177], v0, s[24:25] offset:1024
	v_add_f32_dpp v135, v135, v135 row_ror:8 row_mask:0xf bank_mask:0x3
	s_nop 1
	v_add_f32_dpp v135, v137, v137 row_ror:8 row_mask:0xf bank_mask:0xc
	s_waitcnt lgkmcnt(8)
	v_pk_mul_f32 v[88:89], v[4:5], v[142:143] op_sel_hi:[0,1]
	v_pk_mul_f32 v[90:91], v[6:7], v[146:147] op_sel_hi:[0,1]
	v_pk_fma_f32 v[88:89], v[4:5], v[144:145], v[88:89] op_sel:[1,0,0] op_sel_hi:[1,1,1]
	v_pk_fma_f32 v[90:91], v[6:7], v[148:149], v[90:91] op_sel:[1,0,0] op_sel_hi:[1,1,1]
	v_pk_add_f32 v[102:103], v[88:89], v[90:91]
	s_waitcnt lgkmcnt(7)
	v_pk_mul_f32 v[96:97], v[86:87], v[154:155] op_sel:[0,0] op_sel_hi:[0,1]
	v_pk_mul_f32 v[98:99], v[86:87], v[156:157] op_sel:[0,0] op_sel_hi:[0,1]
	v_add_f32_dpp v93, v102, v102 quad_perm:[1,0,3,2] row_mask:0xf bank_mask:0xf
	s_waitcnt vmcnt(6)
	v_pk_fma_f32 v[96:97], v[4:5], v[182:183], v[96:97]
	v_pk_fma_f32 v[98:99], v[6:7], v[184:185], v[98:99]
	v_add_f32_dpp v92, v93, v93 quad_perm:[2,3,0,1] row_mask:0xf bank_mask:0xf
	s_nop 1
	v_add_f32_dpp v93, v92, v92 row_ror:4 row_mask:0xf bank_mask:0xf
	s_nop 1
	v_add_f32_dpp v94, v93, v93 row_ror:8 row_mask:0xf bank_mask:0xf
	v_add_f32_dpp v111, v93, v93 row_ror:8 row_mask:0xf bank_mask:0x2
	s_waitcnt lgkmcnt(6)
	v_pk_fma_f32 v[4:5], v[94:95], v[150:151], v[96:97] op_sel_hi:[0,1,1] neg_lo:[1,0,0] neg_hi:[1,0,0]
	v_pk_fma_f32 v[6:7], v[94:95], v[152:153], v[98:99] op_sel_hi:[0,1,1] neg_lo:[1,0,0] neg_hi:[1,0,0]
	global_load_dwordx4 v[178:181], v0, s[24:25] offset:1280
	s_waitcnt lgkmcnt(4)
	v_pk_mul_f32 v[88:89], v[4:5], v[44:45] op_sel_hi:[0,1]
	v_pk_mul_f32 v[90:91], v[6:7], v[48:49] op_sel_hi:[0,1]
	v_pk_fma_f32 v[88:89], v[4:5], v[46:47], v[88:89] op_sel:[1,0,0] op_sel_hi:[1,1,1]
	v_pk_fma_f32 v[90:91], v[6:7], v[50:51], v[90:91] op_sel:[1,0,0] op_sel_hi:[1,1,1]
	v_pk_add_f32 v[132:133], v[88:89], v[90:91]
	s_waitcnt lgkmcnt(3)
	v_pk_mul_f32 v[96:97], v[86:87], v[56:57] op_sel:[1,0] op_sel_hi:[1,1]
	v_pk_mul_f32 v[98:99], v[86:87], v[58:59] op_sel:[1,0] op_sel_hi:[1,1]
	v_add_f32_dpp v93, v132, v132 quad_perm:[1,0,3,2] row_mask:0xf bank_mask:0xf
	s_waitcnt vmcnt(6)
	v_pk_fma_f32 v[96:97], v[4:5], v[186:187], v[96:97]
	v_pk_fma_f32 v[98:99], v[6:7], v[188:189], v[98:99]
	v_add_f32_dpp v92, v93, v93 quad_perm:[2,3,0,1] row_mask:0xf bank_mask:0xf
	s_nop 1
	v_add_f32_dpp v93, v92, v92 row_ror:4 row_mask:0xf bank_mask:0xf
	s_nop 1
	v_add_f32_dpp v94, v93, v93 row_ror:8 row_mask:0xf bank_mask:0xf
	v_add_f32_dpp v111, v93, v93 row_ror:8 row_mask:0xf bank_mask:0x8
	s_waitcnt lgkmcnt(2)
	v_pk_fma_f32 v[4:5], v[94:95], v[52:53], v[96:97] op_sel_hi:[0,1,1] neg_lo:[1,0,0] neg_hi:[1,0,0]
	v_pk_fma_f32 v[6:7], v[94:95], v[54:55], v[98:99] op_sel_hi:[0,1,1] neg_lo:[1,0,0] neg_hi:[1,0,0]
	global_load_dwordx4 v[182:185], v0, s[24:25] offset:1536
	v_add_f32_dpp v103, v103, v103 row_ror:8 row_mask:0xf bank_mask:0x3
	s_nop 1
	v_add_f32_dpp v103, v133, v133 row_ror:8 row_mask:0xf bank_mask:0xc
	v_add_f32_dpp v135, v135, v135 row_half_mirror row_mask:0xf bank_mask:0x5
	s_nop 1
	v_add_f32_dpp v135, v103, v103 row_half_mirror row_mask:0xf bank_mask:0xa
	v_cndmask_b32_e64 v106, v135, v105, s[36:37]
	v_cndmask_b32_e64 v107, v105, v135, s[36:37]
	s_nop 1
	v_add_f32_dpp v105, v106, v107 quad_perm:[2,3,0,1] row_mask:0xf bank_mask:0xf
	v_cndmask_b32_e64 v106, v105, v101, s[34:35]
	v_cndmask_b32_e64 v107, v101, v105, s[34:35]
	s_nop 1
	v_add_f32_dpp v101, v106, v107 quad_perm:[1,0,3,2] row_mask:0xf bank_mask:0xf
	v_cndmask_b32_e64 v106, v108, v110, s[34:35]
	v_cndmask_b32_e64 v107, v109, v111, s[34:35]
	v_cndmask_b32_e64 v106, v106, v107, s[36:37]
	s_waitcnt lgkmcnt(0)
	v_fma_f32 v101, v112, v115, v101
	v_fma_f32 v101, -v106, v114, v101
	v_cvt_pk_bf16_f32 v107, v101, v101
	global_store_short v16, v107, s[30:31]
	v_lshlrev_b32_e32 v36, 16, v24
	v_lshlrev_b32_e32 v37, 16, v30
	v_and_b32_e32 v38, 0xffff0000, v24
	v_and_b32_e32 v39, 0xffff0000, v30
	ds_write_b128 v2, v[36:39] offset:21888
	v_lshlrev_b32_e32 v40, 16, v25
	v_lshlrev_b32_e32 v41, 16, v31
	v_and_b32_e32 v42, 0xffff0000, v25
	v_and_b32_e32 v43, 0xffff0000, v31
	ds_write_b128 v2, v[40:43] offset:22144
	v_lshlrev_b32_e32 v44, 16, v26
	v_and_b32_e32 v45, 0xffff0000, v26
	v_lshlrev_b32_e32 v46, 16, v27
	v_and_b32_e32 v47, 0xffff0000, v27
	ds_write_b128 v2, v[44:47] offset:22400
	v_lshlrev_b32_e32 v48, 16, v28
	v_and_b32_e32 v49, 0xffff0000, v28
	v_lshlrev_b32_e32 v50, 16, v29
	v_and_b32_e32 v51, 0xffff0000, v29
	ds_write_b128 v2, v[48:51] offset:22656
	v_lshlrev_b32_e32 v52, 16, v32
	s_cmp_eq_u32 s41, 2
	s_cselect_b32 s2, 0, -1
	v_and_b32_e32 v52, s2, v52
	ds_write_b32 v8, v52 offset:21632
	s_mov_b32 s2, 0x00010001
	s_mov_b32 s3, 0x00010001
	s_mov_b64 exec, s[2:3]
	ds_write_b64 v9, v[34:35] offset:21632
	s_mov_b64 exec, -1
	s_add_u32 s24, s24, 0x1000
	s_addc_u32 s25, s25, 0
	s_add_u32 s26, s26, 0x2800
	s_addc_u32 s27, s27, 0
	s_add_u32 s28, s28, 0x100
	s_addc_u32 s29, s29, 0
	s_add_u32 s30, s30, s40
	s_addc_u32 s31, s31, 0
	s_waitcnt lgkmcnt(0)
	s_barrier
; __device__ __forceinline__ void rwkv_scan2_item(const Params& p, int item, char* ldsraw) {
;     ...
;         for (int q = 0; q < 16; q++) {
;           const f32x4 cw = nw, ckk = nkk, ckka = nkka, ck = nk; const float cvA = nvA, cvB = nvB;
;           if (q < 15) R_LOAD(q + 1)
;           __builtin_amdgcn_sched_barrier(0);
;           float mA0 = mul_s(a0, ckk.x), mA1 = mul_s(a2, ckk.z), mB0 = mul_s(b0, ckk.x), mB1 = mul_s(b2, ckk.z);
;           mA0 = fma_s(a1, ckk.y, mA0); mA1 = fma_s(a3, ckk.w, mA1); mB0 = fma_s(b1, ckk.y, mB0); mB1 = fma_s(b3, ckk.w, mB1);
;           float psA = add_s(mA0, mA1), psB = add_s(mB0, mB1);
;           psA = row16_sum(psA); psB = row16_sum(psB);
;           { const float t0 = fnma_s(psA, ckka.x, mul_s(cvA, ck.x)), t1 = fnma_s(psA, ckka.y, mul_s(cvA, ck.y));
;             const float t2 = fnma_s(psA, ckka.z, mul_s(cvA, ck.z)), t3 = fnma_s(psA, ckka.w, mul_s(cvA, ck.w));
;             a0 = fma_s(a0, cw.x, t0); a1 = fma_s(a1, cw.y, t1); a2 = fma_s(a2, cw.z, t2); a3 = fma_s(a3, cw.w, t3); }
;           { const float t0 = fnma_s(psB, ckka.x, mul_s(cvB, ck.x)), t1 = fnma_s(psB, ckka.y, mul_s(cvB, ck.y));
;             const float t2 = fnma_s(psB, ckka.z, mul_s(cvB, ck.z)), t3 = fnma_s(psB, ckka.w, mul_s(cvB, ck.w));
;             b0 = fma_s(b0, cw.x, t0); b1 = fma_s(b1, cw.y, t1); b2 = fma_s(b2, cw.z, t2); b3 = fma_s(b3, cw.w, t3); }
;           sakA = sel_eq(sakA, psA, jl, q); sakB = sel_eq(sakB, psB, jl, q);
;     ...
;           float nA0 = mul_s(a0, cwr.x), nA1 = mul_s(a2, cwr.z), nB0 = mul_s(b0, cwr.x), nB1 = mul_s(b2, cwr.z);
;           nA0 = fma_s(a1, cwr.y, nA0); nA1 = fma_s(a3, cwr.w, nA1); nB0 = fma_s(b1, cwr.y, nB0); nB1 = fma_s(b3, cwr.w, nB1);
;           float puA = add_s(nA0, nA1), puB = add_s(nB0, nB1);
;           puA = row16_sum(puA); puB = row16_sum(puB);
;           { const float t0 = fnma_s(psA, ckka.x, mul_s(cvA, ck.x)), t1 = fnma_s(psA, ckka.y, mul_s(cvA, ck.y));
;             const float t2 = fnma_s(psA, ckka.z, mul_s(cvA, ck.z)), t3 = fnma_s(psA, ckka.w, mul_s(cvA, ck.w));
;             a0 = fma_s(a0, cw.x, t0); a1 = fma_s(a1, cw.y, t1); a2 = fma_s(a2, cw.z, t2); a3 = fma_s(a3, cw.w, t3); }
;           { const float t0 = fnma_s(psB, ckka.x, mul_s(cvB, ck.x)), t1 = fnma_s(psB, ckka.y, mul_s(cvB, ck.y));
;             const float t2 = fnma_s(psB, ckka.z, mul_s(cvB, ck.z)), t3 = fnma_s(psB, ckka.w, mul_s(cvB, ck.w));
	global_load_dwordx2 v[24:25], v13, s[26:27]
	global_load_dwordx2 v[26:27], v13, s[26:27] offset:128
	global_load_dwordx2 v[28:29], v13, s[26:27] offset:256
	global_load_dwordx2 v[30:31], v13, s[26:27] offset:384
	global_load_ushort v32, v14, s[26:27]
	global_load_dwordx2 v[34:35], v15, s[28:29]
	ds_read_b128 v[44:47], v0 offset:21888
	ds_read_b128 v[48:51], v0 offset:22144
	ds_read_b128 v[56:59], v0 offset:22656
	ds_read_b128 v[52:55], v0 offset:22400
	ds_read_b128 v[80:83], v1 offset:21632
	ds_read_b128 v[64:67], v0 offset:23168
	ds_read_b128 v[68:71], v0 offset:23424
	ds_read_b128 v[76:79], v0 offset:23936
	ds_read_b128 v[72:75], v0 offset:23680
	s_waitcnt lgkmcnt(7)
	v_pk_mul_f32 v[88:89], v[4:5], v[44:45] op_sel_hi:[0,1]
	v_pk_mul_f32 v[90:91], v[6:7], v[48:49] op_sel_hi:[0,1]
	v_pk_fma_f32 v[88:89], v[4:5], v[46:47], v[88:89] op_sel:[1,0,0] op_sel_hi:[1,1,1]
	v_pk_fma_f32 v[90:91], v[6:7], v[50:51], v[90:91] op_sel:[1,0,0] op_sel_hi:[1,1,1]
	v_pk_add_f32 v[100:101], v[88:89], v[90:91]
	s_waitcnt lgkmcnt(4)
	v_pk_mul_f32 v[96:97], v[80:81], v[56:57] op_sel:[0,0] op_sel_hi:[0,1]
	v_pk_mul_f32 v[98:99], v[80:81], v[58:59] op_sel:[0,0] op_sel_hi:[0,1]
	v_add_f32_dpp v93, v100, v100 quad_perm:[1,0,3,2] row_mask:0xf bank_mask:0xf
	s_waitcnt vmcnt(12)
	v_pk_fma_f32 v[96:97], v[4:5], v[158:159], v[96:97]
	v_pk_fma_f32 v[98:99], v[6:7], v[160:161], v[98:99]
	v_add_f32_dpp v92, v93, v93 quad_perm:[2,3,0,1] row_mask:0xf bank_mask:0xf
	ds_read_b128 v[142:145], v0 offset:24448
	ds_read_b128 v[146:149], v0 offset:24704
	v_add_f32_dpp v93, v92, v92 row_ror:4 row_mask:0xf bank_mask:0xf
	ds_read_b128 v[154:157], v0 offset:25216
	ds_read_b128 v[150:153], v0 offset:24960
	v_add_f32_dpp v94, v93, v93 row_ror:8 row_mask:0xf bank_mask:0xf
	v_add_f32_dpp v108, v93, v93 row_ror:8 row_mask:0xf bank_mask:0x1
	v_pk_fma_f32 v[4:5], v[94:95], v[52:53], v[96:97] op_sel_hi:[0,1,1] neg_lo:[1,0,0] neg_hi:[1,0,0]
	v_pk_fma_f32 v[6:7], v[94:95], v[54:55], v[98:99] op_sel_hi:[0,1,1] neg_lo:[1,0,0] neg_hi:[1,0,0]
	global_load_dwordx4 v[186:189], v0, s[24:25] offset:-2304
	s_waitcnt lgkmcnt(6)
	v_pk_mul_f32 v[88:89], v[4:5], v[64:65] op_sel_hi:[0,1]
	v_pk_mul_f32 v[90:91], v[6:7], v[68:69] op_sel_hi:[0,1]
	v_pk_fma_f32 v[88:89], v[4:5], v[66:67], v[88:89] op_sel:[1,0,0] op_sel_hi:[1,1,1]
	v_pk_fma_f32 v[90:91], v[6:7], v[70:71], v[90:91] op_sel:[1,0,0] op_sel_hi:[1,1,1]
	v_pk_add_f32 v[102:103], v[88:89], v[90:91]
	s_waitcnt lgkmcnt(5)
	v_pk_mul_f32 v[96:97], v[80:81], v[76:77] op_sel:[1,0] op_sel_hi:[1,1]
	v_pk_mul_f32 v[98:99], v[80:81], v[78:79] op_sel:[1,0] op_sel_hi:[1,1]
	v_add_f32_dpp v93, v102, v102 quad_perm:[1,0,3,2] row_mask:0xf bank_mask:0xf
	s_waitcnt vmcnt(12)
	v_pk_fma_f32 v[96:97], v[4:5], v[162:163], v[96:97]
	v_pk_fma_f32 v[98:99], v[6:7], v[164:165], v[98:99]
	v_add_f32_dpp v92, v93, v93 quad_perm:[2,3,0,1] row_mask:0xf bank_mask:0xf
	ds_read_b128 v[44:47], v0 offset:25728
	ds_read_b128 v[48:51], v0 offset:25984
	v_add_f32_dpp v93, v92, v92 row_ror:4 row_mask:0xf bank_mask:0xf
	ds_read_b128 v[56:59], v0 offset:26496
	ds_read_b128 v[52:55], v0 offset:26240
	v_add_f32_dpp v94, v93, v93 row_ror:8 row_mask:0xf bank_mask:0xf
	v_add_f32_dpp v108, v93, v93 row_ror:8 row_mask:0xf bank_mask:0x4
	ds_read_b128 v[84:87], v1 offset:21648
	s_waitcnt lgkmcnt(9)
	v_pk_fma_f32 v[4:5], v[94:95], v[72:73], v[96:97] op_sel_hi:[0,1,1] neg_lo:[1,0,0] neg_hi:[1,0,0]
	v_pk_fma_f32 v[6:7], v[94:95], v[74:75], v[98:99] op_sel_hi:[0,1,1] neg_lo:[1,0,0] neg_hi:[1,0,0]
	global_load_dwordx4 v[158:161], v0, s[24:25] offset:-2048
	v_add_f32_dpp v101, v101, v101 row_ror:8 row_mask:0xf bank_mask:0x3
	s_nop 1
	v_add_f32_dpp v101, v103, v103 row_ror:8 row_mask:0xf bank_mask:0xc
	s_waitcnt lgkmcnt(7)
	v_pk_mul_f32 v[88:89], v[4:5], v[142:143] op_sel_hi:[0,1]
	v_pk_mul_f32 v[90:91], v[6:7], v[146:147] op_sel_hi:[0,1]
	v_pk_fma_f32 v[88:89], v[4:5], v[144:145], v[88:89] op_sel:[1,0,0] op_sel_hi:[1,1,1]
	v_pk_fma_f32 v[90:91], v[6:7], v[148:149], v[90:91] op_sel:[1,0,0] op_sel_hi:[1,1,1]
	v_pk_add_f32 v[104:105], v[88:89], v[90:91]
	s_waitcnt lgkmcnt(6)
	v_pk_mul_f32 v[96:97], v[82:83], v[154:155] op_sel:[0,0] op_sel_hi:[0,1]
	v_pk_mul_f32 v[98:99], v[82:83], v[156:157] op_sel:[0,0] op_sel_hi:[0,1]
	v_add_f32_dpp v93, v104, v104 quad_perm:[1,0,3,2] row_mask:0xf bank_mask:0xf
	s_waitcnt vmcnt(12)
	v_pk_fma_f32 v[96:97], v[4:5], v[166:167], v[96:97]
	v_pk_fma_f32 v[98:99], v[6:7], v[168:169], v[98:99]
	v_add_f32_dpp v92, v93, v93 quad_perm:[2,3,0,1] row_mask:0xf bank_mask:0xf
	ds_read_b128 v[64:67], v0 offset:27008
	ds_read_b128 v[68:71], v0 offset:27264
	v_add_f32_dpp v93, v92, v92 row_ror:4 row_mask:0xf bank_mask:0xf
	ds_read_b128 v[76:79], v0 offset:27776
	ds_read_b128 v[72:75], v0 offset:27520
	v_add_f32_dpp v94, v93, v93 row_ror:8 row_mask:0xf bank_mask:0xf
	v_add_f32_dpp v108, v93, v93 row_ror:8 row_mask:0xf bank_mask:0x2
	s_waitcnt lgkmcnt(9)
	v_pk_fma_f32 v[4:5], v[94:95], v[150:151], v[96:97] op_sel_hi:[0,1,1] neg_lo:[1,0,0] neg_hi:[1,0,0]
	v_pk_fma_f32 v[6:7], v[94:95], v[152:153], v[98:99] op_sel_hi:[0,1,1] neg_lo:[1,0,0] neg_hi:[1,0,0]
	global_load_dwordx4 v[162:165], v0, s[24:25] offset:-1792
	s_waitcnt lgkmcnt(7)
	v_pk_mul_f32 v[88:89], v[4:5], v[44:45] op_sel_hi:[0,1]
	v_pk_mul_f32 v[90:91], v[6:7], v[48:49] op_sel_hi:[0,1]
	v_pk_fma_f32 v[88:89], v[4:5], v[46:47], v[88:89] op_sel:[1,0,0] op_sel_hi:[1,1,1]
	v_pk_fma_f32 v[90:91], v[6:7], v[50:51], v[90:91] op_sel:[1,0,0] op_sel_hi:[1,1,1]
	v_pk_add_f32 v[132:133], v[88:89], v[90:91]
	s_waitcnt lgkmcnt(6)
; __device__ __forceinline__ void rwkv_scan2_item(const Params& p, int item, char* ldsraw) {
;     ...
;         for (int q = 0; q < 16; q++) {
;           const f32x4 cw = nw, ckk = nkk, ckka = nkka, ck = nk; const float cvA = nvA, cvB = nvB;
;           if (q < 15) R_LOAD(q + 1)
;           __builtin_amdgcn_sched_barrier(0);
;           float mA0 = mul_s(a0, ckk.x), mA1 = mul_s(a2, ckk.z), mB0 = mul_s(b0, ckk.x), mB1 = mul_s(b2, ckk.z);
;           mA0 = fma_s(a1, ckk.y, mA0); mA1 = fma_s(a3, ckk.w, mA1); mB0 = fma_s(b1, ckk.y, mB0); mB1 = fma_s(b3, ckk.w, mB1);
;           float psA = add_s(mA0, mA1), psB = add_s(mB0, mB1);
;           psA = row16_sum(psA); psB = row16_sum(psB);
;           { const float t0 = fnma_s(psA, ckka.x, mul_s(cvA, ck.x)), t1 = fnma_s(psA, ckka.y, mul_s(cvA, ck.y));
;             const float t2 = fnma_s(psA, ckka.z, mul_s(cvA, ck.z)), t3 = fnma_s(psA, ckka.w, mul_s(cvA, ck.w));
;             a0 = fma_s(a0, cw.x, t0); a1 = fma_s(a1, cw.y, t1); a2 = fma_s(a2, cw.z, t2); a3 = fma_s(a3, cw.w, t3); }
;           { const float t0 = fnma_s(psB, ckka.x, mul_s(cvB, ck.x)), t1 = fnma_s(psB, ckka.y, mul_s(cvB, ck.y));
;             const float t2 = fnma_s(psB, ckka.z, mul_s(cvB, ck.z)), t3 = fnma_s(psB, ckka.w, mul_s(cvB, ck.w));
;             b0 = fma_s(b0, cw.x, t0); b1 = fma_s(b1, cw.y, t1); b2 = fma_s(b2, cw.z, t2); b3 = fma_s(b3, cw.w, t3); }
;           sakA = sel_eq(sakA, psA, jl, q); sakB = sel_eq(sakB, psB, jl, q);
;     ...
;           float nA0 = mul_s(a0, cwr.x), nA1 = mul_s(a2, cwr.z), nB0 = mul_s(b0, cwr.x), nB1 = mul_s(b2, cwr.z);
;           nA0 = fma_s(a1, cwr.y, nA0); nA1 = fma_s(a3, cwr.w, nA1); nB0 = fma_s(b1, cwr.y, nB0); nB1 = fma_s(b3, cwr.w, nB1);
;           float puA = add_s(nA0, nA1), puB = add_s(nB0, nB1);
;           puA = row16_sum(puA); puB = row16_sum(puB);
;           { const float t0 = fnma_s(psA, ckka.x, mul_s(cvA, ck.x)), t1 = fnma_s(psA, ckka.y, mul_s(cvA, ck.y));
;             const float t2 = fnma_s(psA, ckka.z, mul_s(cvA, ck.z)), t3 = fnma_s(psA, ckka.w, mul_s(cvA, ck.w));
;             a0 = fma_s(a0, cw.x, t0); a1 = fma_s(a1, cw.y, t1); a2 = fma_s(a2, cw.z, t2); a3 = fma_s(a3, cw.w, t3); }
;           { const float t0 = fnma_s(psB, ckka.x, mul_s(cvB, ck.x)), t1 = fnma_s(psB, ckka.y, mul_s(cvB, ck.y));
;             const float t2 = fnma_s(psB, ckka.z, mul_s(cvB, ck.z)), t3 = fnma_s(psB, ckka.w, mul_s(cvB, ck.w));
	v_pk_mul_f32 v[96:97], v[82:83], v[56:57] op_sel:[1,0] op_sel_hi:[1,1]
	v_pk_mul_f32 v[98:99], v[82:83], v[58:59] op_sel:[1,0] op_sel_hi:[1,1]
	v_add_f32_dpp v93, v132, v132 quad_perm:[1,0,3,2] row_mask:0xf bank_mask:0xf
	s_waitcnt vmcnt(12)
	v_pk_fma_f32 v[96:97], v[4:5], v[170:171], v[96:97]
	v_pk_fma_f32 v[98:99], v[6:7], v[172:173], v[98:99]
	v_add_f32_dpp v92, v93, v93 quad_perm:[2,3,0,1] row_mask:0xf bank_mask:0xf
	ds_read_b128 v[142:145], v0 offset:28288
	ds_read_b128 v[146:149], v0 offset:28544
	v_add_f32_dpp v93, v92, v92 row_ror:4 row_mask:0xf bank_mask:0xf
	ds_read_b128 v[154:157], v0 offset:29056
	ds_read_b128 v[150:153], v0 offset:28800
	v_add_f32_dpp v94, v93, v93 row_ror:8 row_mask:0xf bank_mask:0xf
	v_add_f32_dpp v108, v93, v93 row_ror:8 row_mask:0xf bank_mask:0x8
	s_waitcnt lgkmcnt(9)
	v_pk_fma_f32 v[4:5], v[94:95], v[52:53], v[96:97] op_sel_hi:[0,1,1] neg_lo:[1,0,0] neg_hi:[1,0,0]
	v_pk_fma_f32 v[6:7], v[94:95], v[54:55], v[98:99] op_sel_hi:[0,1,1] neg_lo:[1,0,0] neg_hi:[1,0,0]
	global_load_dwordx4 v[166:169], v0, s[24:25] offset:-1536
	v_add_f32_dpp v105, v105, v105 row_ror:8 row_mask:0xf bank_mask:0x3
	s_nop 1
	v_add_f32_dpp v105, v133, v133 row_ror:8 row_mask:0xf bank_mask:0xc
	v_add_f32_dpp v101, v101, v101 row_half_mirror row_mask:0xf bank_mask:0x5
	s_nop 1
	v_add_f32_dpp v101, v105, v105 row_half_mirror row_mask:0xf bank_mask:0xa
	s_waitcnt lgkmcnt(6)
	v_pk_mul_f32 v[88:89], v[4:5], v[64:65] op_sel_hi:[0,1]
	v_pk_mul_f32 v[90:91], v[6:7], v[68:69] op_sel_hi:[0,1]
	v_pk_fma_f32 v[88:89], v[4:5], v[66:67], v[88:89] op_sel:[1,0,0] op_sel_hi:[1,1,1]
	v_pk_fma_f32 v[90:91], v[6:7], v[70:71], v[90:91] op_sel:[1,0,0] op_sel_hi:[1,1,1]
	v_pk_add_f32 v[134:135], v[88:89], v[90:91]
	s_waitcnt lgkmcnt(5)
	v_pk_mul_f32 v[96:97], v[84:85], v[76:77] op_sel:[0,0] op_sel_hi:[0,1]
	v_pk_mul_f32 v[98:99], v[84:85], v[78:79] op_sel:[0,0] op_sel_hi:[0,1]
	v_add_f32_dpp v93, v134, v134 quad_perm:[1,0,3,2] row_mask:0xf bank_mask:0xf
	s_waitcnt vmcnt(12)
	v_pk_fma_f32 v[96:97], v[4:5], v[174:175], v[96:97]
	v_pk_fma_f32 v[98:99], v[6:7], v[176:177], v[98:99]
	v_add_f32_dpp v92, v93, v93 quad_perm:[2,3,0,1] row_mask:0xf bank_mask:0xf
	ds_read_b128 v[44:47], v0 offset:29568
	ds_read_b128 v[48:51], v0 offset:29824
	v_add_f32_dpp v93, v92, v92 row_ror:4 row_mask:0xf bank_mask:0xf
	ds_read_b128 v[56:59], v0 offset:30336
	ds_read_b128 v[52:55], v0 offset:30080
	v_add_f32_dpp v94, v93, v93 row_ror:8 row_mask:0xf bank_mask:0xf
	v_add_f32_dpp v109, v93, v93 row_ror:8 row_mask:0xf bank_mask:0x1
	s_waitcnt lgkmcnt(8)
	v_pk_fma_f32 v[4:5], v[94:95], v[72:73], v[96:97] op_sel_hi:[0,1,1] neg_lo:[1,0,0] neg_hi:[1,0,0]
	v_pk_fma_f32 v[6:7], v[94:95], v[74:75], v[98:99] op_sel_hi:[0,1,1] neg_lo:[1,0,0] neg_hi:[1,0,0]
	global_load_dwordx4 v[170:173], v0, s[24:25] offset:-1280
	s_waitcnt lgkmcnt(6)
	v_pk_mul_f32 v[88:89], v[4:5], v[142:143] op_sel_hi:[0,1]
	v_pk_mul_f32 v[90:91], v[6:7], v[146:147] op_sel_hi:[0,1]
	v_pk_fma_f32 v[88:89], v[4:5], v[144:145], v[88:89] op_sel:[1,0,0] op_sel_hi:[1,1,1]
	v_pk_fma_f32 v[90:91], v[6:7], v[148:149], v[90:91] op_sel:[1,0,0] op_sel_hi:[1,1,1]
	v_pk_add_f32 v[136:137], v[88:89], v[90:91]
	s_waitcnt lgkmcnt(5)
	v_pk_mul_f32 v[96:97], v[84:85], v[154:155] op_sel:[1,0] op_sel_hi:[1,1]
	v_pk_mul_f32 v[98:99], v[84:85], v[156:157] op_sel:[1,0] op_sel_hi:[1,1]
	v_add_f32_dpp v93, v136, v136 quad_perm:[1,0,3,2] row_mask:0xf bank_mask:0xf
	s_waitcnt vmcnt(12)
	v_pk_fma_f32 v[96:97], v[4:5], v[178:179], v[96:97]
	v_pk_fma_f32 v[98:99], v[6:7], v[180:181], v[98:99]
	v_add_f32_dpp v92, v93, v93 quad_perm:[2,3,0,1] row_mask:0xf bank_mask:0xf
	ds_read_b128 v[64:67], v0 offset:30848
	ds_read_b128 v[68:71], v0 offset:31104
	v_add_f32_dpp v93, v92, v92 row_ror:4 row_mask:0xf bank_mask:0xf
	ds_read_b128 v[76:79], v0 offset:31616
	ds_read_b128 v[72:75], v0 offset:31360
	v_add_f32_dpp v94, v93, v93 row_ror:8 row_mask:0xf bank_mask:0xf
	v_add_f32_dpp v109, v93, v93 row_ror:8 row_mask:0xf bank_mask:0x4
	ds_read_b128 v[80:83], v1 offset:21664
	s_waitcnt lgkmcnt(9)
	v_pk_fma_f32 v[4:5], v[94:95], v[150:151], v[96:97] op_sel_hi:[0,1,1] neg_lo:[1,0,0] neg_hi:[1,0,0]
	v_pk_fma_f32 v[6:7], v[94:95], v[152:153], v[98:99] op_sel_hi:[0,1,1] neg_lo:[1,0,0] neg_hi:[1,0,0]
	global_load_dwordx4 v[174:177], v0, s[24:25] offset:-1024
	v_add_f32_dpp v135, v135, v135 row_ror:8 row_mask:0xf bank_mask:0x3
	s_nop 1
	v_add_f32_dpp v135, v137, v137 row_ror:8 row_mask:0xf bank_mask:0xc
	s_waitcnt lgkmcnt(7)
	v_pk_mul_f32 v[88:89], v[4:5], v[44:45] op_sel_hi:[0,1]
	v_pk_mul_f32 v[90:91], v[6:7], v[48:49] op_sel_hi:[0,1]
	v_pk_fma_f32 v[88:89], v[4:5], v[46:47], v[88:89] op_sel:[1,0,0] op_sel_hi:[1,1,1]
	v_pk_fma_f32 v[90:91], v[6:7], v[50:51], v[90:91] op_sel:[1,0,0] op_sel_hi:[1,1,1]
	v_pk_add_f32 v[102:103], v[88:89], v[90:91]
	s_waitcnt lgkmcnt(6)
	v_pk_mul_f32 v[96:97], v[86:87], v[56:57] op_sel:[0,0] op_sel_hi:[0,1]
	v_pk_mul_f32 v[98:99], v[86:87], v[58:59] op_sel:[0,0] op_sel_hi:[0,1]
	v_add_f32_dpp v93, v102, v102 quad_perm:[1,0,3,2] row_mask:0xf bank_mask:0xf
	s_waitcnt vmcnt(12)
	v_pk_fma_f32 v[96:97], v[4:5], v[182:183], v[96:97]
	v_pk_fma_f32 v[98:99], v[6:7], v[184:185], v[98:99]
	v_add_f32_dpp v92, v93, v93 quad_perm:[2,3,0,1] row_mask:0xf bank_mask:0xf
	ds_read_b128 v[142:145], v0 offset:32128
	ds_read_b128 v[146:149], v0 offset:32384
	v_add_f32_dpp v93, v92, v92 row_ror:4 row_mask:0xf bank_mask:0xf
	ds_read_b128 v[154:157], v0 offset:32896
	ds_read_b128 v[150:153], v0 offset:32640
	v_add_f32_dpp v94, v93, v93 row_ror:8 row_mask:0xf bank_mask:0xf
	v_add_f32_dpp v109, v93, v93 row_ror:8 row_mask:0xf bank_mask:0x2
	s_waitcnt lgkmcnt(9)
; __device__ __forceinline__ void rwkv_scan2_item(const Params& p, int item, char* ldsraw) {
;     ...
;         for (int q = 0; q < 16; q++) {
;           const f32x4 cw = nw, ckk = nkk, ckka = nkka, ck = nk; const float cvA = nvA, cvB = nvB;
;           if (q < 15) R_LOAD(q + 1)
;           __builtin_amdgcn_sched_barrier(0);
;           float mA0 = mul_s(a0, ckk.x), mA1 = mul_s(a2, ckk.z), mB0 = mul_s(b0, ckk.x), mB1 = mul_s(b2, ckk.z);
;           mA0 = fma_s(a1, ckk.y, mA0); mA1 = fma_s(a3, ckk.w, mA1); mB0 = fma_s(b1, ckk.y, mB0); mB1 = fma_s(b3, ckk.w, mB1);
;           float psA = add_s(mA0, mA1), psB = add_s(mB0, mB1);
;           psA = row16_sum(psA); psB = row16_sum(psB);
;           { const float t0 = fnma_s(psA, ckka.x, mul_s(cvA, ck.x)), t1 = fnma_s(psA, ckka.y, mul_s(cvA, ck.y));
;             const float t2 = fnma_s(psA, ckka.z, mul_s(cvA, ck.z)), t3 = fnma_s(psA, ckka.w, mul_s(cvA, ck.w));
;             a0 = fma_s(a0, cw.x, t0); a1 = fma_s(a1, cw.y, t1); a2 = fma_s(a2, cw.z, t2); a3 = fma_s(a3, cw.w, t3); }
;           { const float t0 = fnma_s(psB, ckka.x, mul_s(cvB, ck.x)), t1 = fnma_s(psB, ckka.y, mul_s(cvB, ck.y));
;             const float t2 = fnma_s(psB, ckka.z, mul_s(cvB, ck.z)), t3 = fnma_s(psB, ckka.w, mul_s(cvB, ck.w));
;             b0 = fma_s(b0, cw.x, t0); b1 = fma_s(b1, cw.y, t1); b2 = fma_s(b2, cw.z, t2); b3 = fma_s(b3, cw.w, t3); }
;           sakA = sel_eq(sakA, psA, jl, q); sakB = sel_eq(sakB, psB, jl, q);
;     ...
;           float nA0 = mul_s(a0, cwr.x), nA1 = mul_s(a2, cwr.z), nB0 = mul_s(b0, cwr.x), nB1 = mul_s(b2, cwr.z);
;           nA0 = fma_s(a1, cwr.y, nA0); nA1 = fma_s(a3, cwr.w, nA1); nB0 = fma_s(b1, cwr.y, nB0); nB1 = fma_s(b3, cwr.w, nB1);
;           float puA = add_s(nA0, nA1), puB = add_s(nB0, nB1);
;           puA = row16_sum(puA); puB = row16_sum(puB);
;           { const float t0 = fnma_s(psA, ckka.x, mul_s(cvA, ck.x)), t1 = fnma_s(psA, ckka.y, mul_s(cvA, ck.y));
;             const float t2 = fnma_s(psA, ckka.z, mul_s(cvA, ck.z)), t3 = fnma_s(psA, ckka.w, mul_s(cvA, ck.w));
;             a0 = fma_s(a0, cw.x, t0); a1 = fma_s(a1, cw.y, t1); a2 = fma_s(a2, cw.z, t2); a3 = fma_s(a3, cw.w, t3); }
;           { const float t0 = fnma_s(psB, ckka.x, mul_s(cvB, ck.x)), t1 = fnma_s(psB, ckka.y, mul_s(cvB, ck.y));
;             const float t2 = fnma_s(psB, ckka.z, mul_s(cvB, ck.z)), t3 = fnma_s(psB, ckka.w, mul_s(cvB, ck.w));
	v_pk_fma_f32 v[4:5], v[94:95], v[52:53], v[96:97] op_sel_hi:[0,1,1] neg_lo:[1,0,0] neg_hi:[1,0,0]
	v_pk_fma_f32 v[6:7], v[94:95], v[54:55], v[98:99] op_sel_hi:[0,1,1] neg_lo:[1,0,0] neg_hi:[1,0,0]
	global_load_dwordx4 v[178:181], v0, s[24:25] offset:-768
	s_waitcnt lgkmcnt(7)
	v_pk_mul_f32 v[88:89], v[4:5], v[64:65] op_sel_hi:[0,1]
	v_pk_mul_f32 v[90:91], v[6:7], v[68:69] op_sel_hi:[0,1]
	v_pk_fma_f32 v[88:89], v[4:5], v[66:67], v[88:89] op_sel:[1,0,0] op_sel_hi:[1,1,1]
	v_pk_fma_f32 v[90:91], v[6:7], v[70:71], v[90:91] op_sel:[1,0,0] op_sel_hi:[1,1,1]
	v_pk_add_f32 v[132:133], v[88:89], v[90:91]
	s_waitcnt lgkmcnt(6)
	v_pk_mul_f32 v[96:97], v[86:87], v[76:77] op_sel:[1,0] op_sel_hi:[1,1]
	v_pk_mul_f32 v[98:99], v[86:87], v[78:79] op_sel:[1,0] op_sel_hi:[1,1]
	v_add_f32_dpp v93, v132, v132 quad_perm:[1,0,3,2] row_mask:0xf bank_mask:0xf
	s_waitcnt vmcnt(6)
	v_pk_fma_f32 v[96:97], v[4:5], v[186:187], v[96:97]
	v_pk_fma_f32 v[98:99], v[6:7], v[188:189], v[98:99]
	v_add_f32_dpp v92, v93, v93 quad_perm:[2,3,0,1] row_mask:0xf bank_mask:0xf
	ds_read_b128 v[44:47], v0 offset:33408
	ds_read_b128 v[48:51], v0 offset:33664
	v_add_f32_dpp v93, v92, v92 row_ror:4 row_mask:0xf bank_mask:0xf
	ds_read_b128 v[56:59], v0 offset:34176
	ds_read_b128 v[52:55], v0 offset:33920
	v_add_f32_dpp v94, v93, v93 row_ror:8 row_mask:0xf bank_mask:0xf
	v_add_f32_dpp v109, v93, v93 row_ror:8 row_mask:0xf bank_mask:0x8
	s_waitcnt lgkmcnt(9)
	v_pk_fma_f32 v[4:5], v[94:95], v[72:73], v[96:97] op_sel_hi:[0,1,1] neg_lo:[1,0,0] neg_hi:[1,0,0]
	v_pk_fma_f32 v[6:7], v[94:95], v[74:75], v[98:99] op_sel_hi:[0,1,1] neg_lo:[1,0,0] neg_hi:[1,0,0]
	global_load_dwordx4 v[182:185], v0, s[24:25] offset:-512
	v_add_f32_dpp v103, v103, v103 row_ror:8 row_mask:0xf bank_mask:0x3
	s_nop 1
	v_add_f32_dpp v103, v133, v133 row_ror:8 row_mask:0xf bank_mask:0xc
	v_add_f32_dpp v135, v135, v135 row_half_mirror row_mask:0xf bank_mask:0x5
	s_nop 1
	v_add_f32_dpp v135, v103, v103 row_half_mirror row_mask:0xf bank_mask:0xa
	v_cndmask_b32_e64 v106, v135, v101, s[36:37]
	v_cndmask_b32_e64 v107, v101, v135, s[36:37]
	s_nop 1
	v_add_f32_dpp v101, v106, v107 quad_perm:[2,3,0,1] row_mask:0xf bank_mask:0xf
	s_waitcnt lgkmcnt(6)
	v_pk_mul_f32 v[88:89], v[4:5], v[142:143] op_sel_hi:[0,1]
	v_pk_mul_f32 v[90:91], v[6:7], v[146:147] op_sel_hi:[0,1]
	v_pk_fma_f32 v[88:89], v[4:5], v[144:145], v[88:89] op_sel:[1,0,0] op_sel_hi:[1,1,1]
	v_pk_fma_f32 v[90:91], v[6:7], v[148:149], v[90:91] op_sel:[1,0,0] op_sel_hi:[1,1,1]
	v_pk_add_f32 v[104:105], v[88:89], v[90:91]
	s_waitcnt lgkmcnt(5)
	v_pk_mul_f32 v[96:97], v[80:81], v[154:155] op_sel:[0,0] op_sel_hi:[0,1]
	v_pk_mul_f32 v[98:99], v[80:81], v[156:157] op_sel:[0,0] op_sel_hi:[0,1]
	v_add_f32_dpp v93, v104, v104 quad_perm:[1,0,3,2] row_mask:0xf bank_mask:0xf
	s_waitcnt vmcnt(6)
	v_pk_fma_f32 v[96:97], v[4:5], v[158:159], v[96:97]
	v_pk_fma_f32 v[98:99], v[6:7], v[160:161], v[98:99]
	v_add_f32_dpp v92, v93, v93 quad_perm:[2,3,0,1] row_mask:0xf bank_mask:0xf
	ds_read_b128 v[64:67], v0 offset:34688
	ds_read_b128 v[68:71], v0 offset:34944
	v_add_f32_dpp v93, v92, v92 row_ror:4 row_mask:0xf bank_mask:0xf
	ds_read_b128 v[76:79], v0 offset:35456
	ds_read_b128 v[72:75], v0 offset:35200
	v_add_f32_dpp v94, v93, v93 row_ror:8 row_mask:0xf bank_mask:0xf
	v_add_f32_dpp v110, v93, v93 row_ror:8 row_mask:0xf bank_mask:0x1
	s_waitcnt lgkmcnt(8)
	v_pk_fma_f32 v[4:5], v[94:95], v[150:151], v[96:97] op_sel_hi:[0,1,1] neg_lo:[1,0,0] neg_hi:[1,0,0]
	v_pk_fma_f32 v[6:7], v[94:95], v[152:153], v[98:99] op_sel_hi:[0,1,1] neg_lo:[1,0,0] neg_hi:[1,0,0]
	global_load_dwordx4 v[186:189], v0, s[24:25] offset:-256
	s_waitcnt lgkmcnt(6)
	v_pk_mul_f32 v[88:89], v[4:5], v[44:45] op_sel_hi:[0,1]
	v_pk_mul_f32 v[90:91], v[6:7], v[48:49] op_sel_hi:[0,1]
	v_pk_fma_f32 v[88:89], v[4:5], v[46:47], v[88:89] op_sel:[1,0,0] op_sel_hi:[1,1,1]
	v_pk_fma_f32 v[90:91], v[6:7], v[50:51], v[90:91] op_sel:[1,0,0] op_sel_hi:[1,1,1]
	v_pk_add_f32 v[136:137], v[88:89], v[90:91]
	s_waitcnt lgkmcnt(5)
	v_pk_mul_f32 v[96:97], v[80:81], v[56:57] op_sel:[1,0] op_sel_hi:[1,1]
	v_pk_mul_f32 v[98:99], v[80:81], v[58:59] op_sel:[1,0] op_sel_hi:[1,1]
	v_add_f32_dpp v93, v136, v136 quad_perm:[1,0,3,2] row_mask:0xf bank_mask:0xf
	s_waitcnt vmcnt(6)
	v_pk_fma_f32 v[96:97], v[4:5], v[162:163], v[96:97]
	v_pk_fma_f32 v[98:99], v[6:7], v[164:165], v[98:99]
	v_add_f32_dpp v92, v93, v93 quad_perm:[2,3,0,1] row_mask:0xf bank_mask:0xf
	ds_read_b128 v[142:145], v0 offset:35968
	ds_read_b128 v[146:149], v0 offset:36224
	v_add_f32_dpp v93, v92, v92 row_ror:4 row_mask:0xf bank_mask:0xf
	ds_read_b128 v[154:157], v0 offset:36736
	ds_read_b128 v[150:153], v0 offset:36480
	v_add_f32_dpp v94, v93, v93 row_ror:8 row_mask:0xf bank_mask:0xf
	v_add_f32_dpp v110, v93, v93 row_ror:8 row_mask:0xf bank_mask:0x4
	ds_read_b128 v[84:87], v1 offset:21680
	s_waitcnt lgkmcnt(9)
	v_pk_fma_f32 v[4:5], v[94:95], v[52:53], v[96:97] op_sel_hi:[0,1,1] neg_lo:[1,0,0] neg_hi:[1,0,0]
	v_pk_fma_f32 v[6:7], v[94:95], v[54:55], v[98:99] op_sel_hi:[0,1,1] neg_lo:[1,0,0] neg_hi:[1,0,0]
	global_load_dwordx4 v[158:161], v0, s[24:25] offset:0
	v_add_f32_dpp v105, v105, v105 row_ror:8 row_mask:0xf bank_mask:0x3
	s_nop 1
	v_add_f32_dpp v105, v137, v137 row_ror:8 row_mask:0xf bank_mask:0xc
	s_waitcnt lgkmcnt(7)
	v_pk_mul_f32 v[88:89], v[4:5], v[64:65] op_sel_hi:[0,1]
	v_pk_mul_f32 v[90:91], v[6:7], v[68:69] op_sel_hi:[0,1]
	v_pk_fma_f32 v[88:89], v[4:5], v[66:67], v[88:89] op_sel:[1,0,0] op_sel_hi:[1,1,1]
	v_pk_fma_f32 v[90:91], v[6:7], v[70:71], v[90:91] op_sel:[1,0,0] op_sel_hi:[1,1,1]
	v_pk_add_f32 v[132:133], v[88:89], v[90:91]
	s_waitcnt lgkmcnt(6)
; __device__ __forceinline__ void rwkv_scan2_item(const Params& p, int item, char* ldsraw) {
;     ...
;         for (int q = 0; q < 16; q++) {
;           const f32x4 cw = nw, ckk = nkk, ckka = nkka, ck = nk; const float cvA = nvA, cvB = nvB;
;           if (q < 15) R_LOAD(q + 1)
;           __builtin_amdgcn_sched_barrier(0);
;           float mA0 = mul_s(a0, ckk.x), mA1 = mul_s(a2, ckk.z), mB0 = mul_s(b0, ckk.x), mB1 = mul_s(b2, ckk.z);
;           mA0 = fma_s(a1, ckk.y, mA0); mA1 = fma_s(a3, ckk.w, mA1); mB0 = fma_s(b1, ckk.y, mB0); mB1 = fma_s(b3, ckk.w, mB1);
;           float psA = add_s(mA0, mA1), psB = add_s(mB0, mB1);
;           psA = row16_sum(psA); psB = row16_sum(psB);
;           { const float t0 = fnma_s(psA, ckka.x, mul_s(cvA, ck.x)), t1 = fnma_s(psA, ckka.y, mul_s(cvA, ck.y));
;             const float t2 = fnma_s(psA, ckka.z, mul_s(cvA, ck.z)), t3 = fnma_s(psA, ckka.w, mul_s(cvA, ck.w));
;             a0 = fma_s(a0, cw.x, t0); a1 = fma_s(a1, cw.y, t1); a2 = fma_s(a2, cw.z, t2); a3 = fma_s(a3, cw.w, t3); }
;           { const float t0 = fnma_s(psB, ckka.x, mul_s(cvB, ck.x)), t1 = fnma_s(psB, ckka.y, mul_s(cvB, ck.y));
;             const float t2 = fnma_s(psB, ckka.z, mul_s(cvB, ck.z)), t3 = fnma_s(psB, ckka.w, mul_s(cvB, ck.w));
;             b0 = fma_s(b0, cw.x, t0); b1 = fma_s(b1, cw.y, t1); b2 = fma_s(b2, cw.z, t2); b3 = fma_s(b3, cw.w, t3); }
;           sakA = sel_eq(sakA, psA, jl, q); sakB = sel_eq(sakB, psB, jl, q);
;     ...
;           float nA0 = mul_s(a0, cwr.x), nA1 = mul_s(a2, cwr.z), nB0 = mul_s(b0, cwr.x), nB1 = mul_s(b2, cwr.z);
;           nA0 = fma_s(a1, cwr.y, nA0); nA1 = fma_s(a3, cwr.w, nA1); nB0 = fma_s(b1, cwr.y, nB0); nB1 = fma_s(b3, cwr.w, nB1);
;           float puA = add_s(nA0, nA1), puB = add_s(nB0, nB1);
;           puA = row16_sum(puA); puB = row16_sum(puB);
;           { const float t0 = fnma_s(psA, ckka.x, mul_s(cvA, ck.x)), t1 = fnma_s(psA, ckka.y, mul_s(cvA, ck.y));
;             const float t2 = fnma_s(psA, ckka.z, mul_s(cvA, ck.z)), t3 = fnma_s(psA, ckka.w, mul_s(cvA, ck.w));
;             a0 = fma_s(a0, cw.x, t0); a1 = fma_s(a1, cw.y, t1); a2 = fma_s(a2, cw.z, t2); a3 = fma_s(a3, cw.w, t3); }
;           { const float t0 = fnma_s(psB, ckka.x, mul_s(cvB, ck.x)), t1 = fnma_s(psB, ckka.y, mul_s(cvB, ck.y));
;             const float t2 = fnma_s(psB, ckka.z, mul_s(cvB, ck.z)), t3 = fnma_s(psB, ckka.w, mul_s(cvB, ck.w));
	v_pk_mul_f32 v[96:97], v[82:83], v[76:77] op_sel:[0,0] op_sel_hi:[0,1]
	v_pk_mul_f32 v[98:99], v[82:83], v[78:79] op_sel:[0,0] op_sel_hi:[0,1]
	v_add_f32_dpp v93, v132, v132 quad_perm:[1,0,3,2] row_mask:0xf bank_mask:0xf
	s_waitcnt vmcnt(6)
	v_pk_fma_f32 v[96:97], v[4:5], v[166:167], v[96:97]
	v_pk_fma_f32 v[98:99], v[6:7], v[168:169], v[98:99]
	v_add_f32_dpp v92, v93, v93 quad_perm:[2,3,0,1] row_mask:0xf bank_mask:0xf
	ds_read_b128 v[44:47], v0 offset:37248
	ds_read_b128 v[48:51], v0 offset:37504
	v_add_f32_dpp v93, v92, v92 row_ror:4 row_mask:0xf bank_mask:0xf
	ds_read_b128 v[56:59], v0 offset:38016
	ds_read_b128 v[52:55], v0 offset:37760
	v_add_f32_dpp v94, v93, v93 row_ror:8 row_mask:0xf bank_mask:0xf
	v_add_f32_dpp v110, v93, v93 row_ror:8 row_mask:0xf bank_mask:0x2
	s_waitcnt lgkmcnt(9)
	v_pk_fma_f32 v[4:5], v[94:95], v[72:73], v[96:97] op_sel_hi:[0,1,1] neg_lo:[1,0,0] neg_hi:[1,0,0]
	v_pk_fma_f32 v[6:7], v[94:95], v[74:75], v[98:99] op_sel_hi:[0,1,1] neg_lo:[1,0,0] neg_hi:[1,0,0]
	global_load_dwordx4 v[162:165], v0, s[24:25] offset:256
	s_waitcnt lgkmcnt(7)
	v_pk_mul_f32 v[88:89], v[4:5], v[142:143] op_sel_hi:[0,1]
	v_pk_mul_f32 v[90:91], v[6:7], v[146:147] op_sel_hi:[0,1]
	v_pk_fma_f32 v[88:89], v[4:5], v[144:145], v[88:89] op_sel:[1,0,0] op_sel_hi:[1,1,1]
	v_pk_fma_f32 v[90:91], v[6:7], v[148:149], v[90:91] op_sel:[1,0,0] op_sel_hi:[1,1,1]
	v_pk_add_f32 v[102:103], v[88:89], v[90:91]
	s_waitcnt lgkmcnt(6)
	v_pk_mul_f32 v[96:97], v[82:83], v[154:155] op_sel:[1,0] op_sel_hi:[1,1]
	v_pk_mul_f32 v[98:99], v[82:83], v[156:157] op_sel:[1,0] op_sel_hi:[1,1]
	v_add_f32_dpp v93, v102, v102 quad_perm:[1,0,3,2] row_mask:0xf bank_mask:0xf
	s_waitcnt vmcnt(6)
	v_pk_fma_f32 v[96:97], v[4:5], v[170:171], v[96:97]
	v_pk_fma_f32 v[98:99], v[6:7], v[172:173], v[98:99]
	v_add_f32_dpp v92, v93, v93 quad_perm:[2,3,0,1] row_mask:0xf bank_mask:0xf
	ds_read_b128 v[64:67], v0 offset:38528
	ds_read_b128 v[68:71], v0 offset:38784
	v_add_f32_dpp v93, v92, v92 row_ror:4 row_mask:0xf bank_mask:0xf
	ds_read_b128 v[76:79], v0 offset:39296
	ds_read_b128 v[72:75], v0 offset:39040
	v_add_f32_dpp v94, v93, v93 row_ror:8 row_mask:0xf bank_mask:0xf
	v_add_f32_dpp v110, v93, v93 row_ror:8 row_mask:0xf bank_mask:0x8
	s_waitcnt lgkmcnt(9)
	v_pk_fma_f32 v[4:5], v[94:95], v[150:151], v[96:97] op_sel_hi:[0,1,1] neg_lo:[1,0,0] neg_hi:[1,0,0]
	v_pk_fma_f32 v[6:7], v[94:95], v[152:153], v[98:99] op_sel_hi:[0,1,1] neg_lo:[1,0,0] neg_hi:[1,0,0]
	global_load_dwordx4 v[166:169], v0, s[24:25] offset:512
	v_add_f32_dpp v133, v133, v133 row_ror:8 row_mask:0xf bank_mask:0x3
	s_nop 1
	v_add_f32_dpp v133, v103, v103 row_ror:8 row_mask:0xf bank_mask:0xc
	v_add_f32_dpp v105, v105, v105 row_half_mirror row_mask:0xf bank_mask:0x5
	s_nop 1
	v_add_f32_dpp v105, v133, v133 row_half_mirror row_mask:0xf bank_mask:0xa
	s_waitcnt lgkmcnt(6)
	v_pk_mul_f32 v[88:89], v[4:5], v[44:45] op_sel_hi:[0,1]
	v_pk_mul_f32 v[90:91], v[6:7], v[48:49] op_sel_hi:[0,1]
	v_pk_fma_f32 v[88:89], v[4:5], v[46:47], v[88:89] op_sel:[1,0,0] op_sel_hi:[1,1,1]
	v_pk_fma_f32 v[90:91], v[6:7], v[50:51], v[90:91] op_sel:[1,0,0] op_sel_hi:[1,1,1]
	v_pk_add_f32 v[134:135], v[88:89], v[90:91]
	s_waitcnt lgkmcnt(5)
	v_pk_mul_f32 v[96:97], v[84:85], v[56:57] op_sel:[0,0] op_sel_hi:[0,1]
	v_pk_mul_f32 v[98:99], v[84:85], v[58:59] op_sel:[0,0] op_sel_hi:[0,1]
	v_add_f32_dpp v93, v134, v134 quad_perm:[1,0,3,2] row_mask:0xf bank_mask:0xf
	s_waitcnt vmcnt(6)
	v_pk_fma_f32 v[96:97], v[4:5], v[174:175], v[96:97]
	v_pk_fma_f32 v[98:99], v[6:7], v[176:177], v[98:99]
	v_add_f32_dpp v92, v93, v93 quad_perm:[2,3,0,1] row_mask:0xf bank_mask:0xf
	ds_read_b128 v[142:145], v0 offset:39808
	ds_read_b128 v[146:149], v0 offset:40064
	v_add_f32_dpp v93, v92, v92 row_ror:4 row_mask:0xf bank_mask:0xf
	ds_read_b128 v[154:157], v0 offset:40576
	ds_read_b128 v[150:153], v0 offset:40320
	v_add_f32_dpp v94, v93, v93 row_ror:8 row_mask:0xf bank_mask:0xf
	v_add_f32_dpp v111, v93, v93 row_ror:8 row_mask:0xf bank_mask:0x1
	s_waitcnt lgkmcnt(8)
	v_pk_fma_f32 v[4:5], v[94:95], v[52:53], v[96:97] op_sel_hi:[0,1,1] neg_lo:[1,0,0] neg_hi:[1,0,0]
	v_pk_fma_f32 v[6:7], v[94:95], v[54:55], v[98:99] op_sel_hi:[0,1,1] neg_lo:[1,0,0] neg_hi:[1,0,0]
	global_load_dwordx4 v[170:173], v0, s[24:25] offset:768
	s_waitcnt lgkmcnt(6)
	v_pk_mul_f32 v[88:89], v[4:5], v[64:65] op_sel_hi:[0,1]
	v_pk_mul_f32 v[90:91], v[6:7], v[68:69] op_sel_hi:[0,1]
	v_pk_fma_f32 v[88:89], v[4:5], v[66:67], v[88:89] op_sel:[1,0,0] op_sel_hi:[1,1,1]
	v_pk_fma_f32 v[90:91], v[6:7], v[70:71], v[90:91] op_sel:[1,0,0] op_sel_hi:[1,1,1]
	v_pk_add_f32 v[136:137], v[88:89], v[90:91]
	s_waitcnt lgkmcnt(5)
	v_pk_mul_f32 v[96:97], v[84:85], v[76:77] op_sel:[1,0] op_sel_hi:[1,1]
	v_pk_mul_f32 v[98:99], v[84:85], v[78:79] op_sel:[1,0] op_sel_hi:[1,1]
	v_add_f32_dpp v93, v136, v136 quad_perm:[1,0,3,2] row_mask:0xf bank_mask:0xf
	s_waitcnt vmcnt(6)
	v_pk_fma_f32 v[96:97], v[4:5], v[178:179], v[96:97]
	v_pk_fma_f32 v[98:99], v[6:7], v[180:181], v[98:99]
	v_add_f32_dpp v92, v93, v93 quad_perm:[2,3,0,1] row_mask:0xf bank_mask:0xf
	ds_read_b128 v[44:47], v0 offset:41088
	ds_read_b128 v[48:51], v0 offset:41344
	v_add_f32_dpp v93, v92, v92 row_ror:4 row_mask:0xf bank_mask:0xf
	ds_read_b128 v[56:59], v0 offset:41856
	ds_read_b128 v[52:55], v0 offset:41600
	v_add_f32_dpp v94, v93, v93 row_ror:8 row_mask:0xf bank_mask:0xf
	v_add_f32_dpp v111, v93, v93 row_ror:8 row_mask:0xf bank_mask:0x4
	ds_read_b32 v112, v10 offset:21632
	s_waitcnt lgkmcnt(9)
; __device__ __forceinline__ unsigned char* WS(const Params& p) { unsigned z = 0; asm volatile("" : "+s"(z)); return p.ws + z; }
; __device__ __forceinline__ float bf2f(unsigned short b) { return __uint_as_float(((unsigned)b) << 16); }
; __device__ __forceinline__ unsigned short f2bf(float f) { unsigned r; asm("v_cvt_pk_bf16_f32 %0, %1, %1" : "=v"(r) : "v"(f)); return (unsigned short)(r & 0xffffu); }
; __device__ __forceinline__ float bflo(unsigned u) { return __uint_as_float(u << 16); }
; __device__ __forceinline__ float bfhi(unsigned u) { return __uint_as_float(u & 0xffff0000u); }
; __device__ __forceinline__ float fma_s(float a, float b, float c) { float d; asm("v_fma_f32 %0, %1, %2, %3" : "=v"(d) : "v"(a), "v"(b), "v"(c)); return d; }
; __device__ __forceinline__ float fnma_s(float a, float b, float c) { float d; asm("v_fma_f32 %0, -%1, %2, %3" : "=v"(d) : "v"(a), "v"(b), "v"(c)); return d; }
; __device__ __forceinline__ void rwkv_scan2_item(const Params& p, int item, char* ldsraw) {
;     ...
;   auto store = [&](int bi) {
;     float* d = buf + bi * CH + st * STEP;
;     *(f32x4*)(d + part * 4) = pw;
;     *(f32x4*)(d + 64 + part * 4) = (f32x4){bflo(pkk[0]), bfhi(pkk[0]), bflo(pkk[1]), bfhi(pkk[1])};
;     *(f32x4*)(d + 128 + part * 4) = (f32x4){bflo(pkka[0]), bfhi(pkka[0]), bflo(pkka[1]), bfhi(pkka[1])};
;     *(f32x4*)(d + 192 + part * 4) = (f32x4){bflo(pk[0]), bfhi(pk[0]), bflo(pk[1]), bfhi(pk[1])};
;     *(f32x4*)(d + 256 + part * 4) = (f32x4){bflo(pwr[0]), bfhi(pwr[0]), bflo(pwr[1]), bfhi(pwr[1])};
;     d[320 + part] = ident ? 0.f : bf2f(pv);
;     if (part < 2) d[336 + part] = pc;
;   };
;     ...
;           const float yA = fnma_s(psA, ccc.x, fma_s(cvA, ccc.y, puA)), yB = fnma_s(psB, ccc.x, fma_s(cvB, ccc.y, puB));
;           ykA = sel_eq(ykA, yA, jl, q); ykB = sel_eq(ykB, yB, jl, q);
;         }
;     ...
;         yout[(size_t)(c - 1) * ystride] = f2bf(ykA); yout[(size_t)(c - 1) * ystride + 8] = f2bf(ykB);
;       }
;     }
;     if (c + 1 < 128) store(bnext);
;     bi = bnext;
;     asm volatile("s_waitcnt lgkmcnt(0)" ::: "memory"); __builtin_amdgcn_s_barrier(); asm volatile("" ::: "memory");
;   }
;   if (seg == 0 && !isY) {
;     float* sf = (float*)(WS(p) + OFF_SF) + ((size_t)bh * 64 + rowA) * 64 + jl * 4;
;     *(f32x4*)sf = (f32x4){a0, a1, a2, a3}; *(f32x4*)(sf + 8 * 64) = (f32x4){b0, b1, b2, b3};
;   }
	v_pk_fma_f32 v[4:5], v[94:95], v[72:73], v[96:97] op_sel_hi:[0,1,1] neg_lo:[1,0,0] neg_hi:[1,0,0]
	v_pk_fma_f32 v[6:7], v[94:95], v[74:75], v[98:99] op_sel_hi:[0,1,1] neg_lo:[1,0,0] neg_hi:[1,0,0]
	ds_read_b64 v[114:115], v11 offset:21632
	global_load_dwordx4 v[174:177], v0, s[24:25] offset:1024
	v_add_f32_dpp v135, v135, v135 row_ror:8 row_mask:0xf bank_mask:0x3
	s_nop 1
	v_add_f32_dpp v135, v137, v137 row_ror:8 row_mask:0xf bank_mask:0xc
	s_waitcnt lgkmcnt(8)
	v_pk_mul_f32 v[88:89], v[4:5], v[142:143] op_sel_hi:[0,1]
	v_pk_mul_f32 v[90:91], v[6:7], v[146:147] op_sel_hi:[0,1]
	v_pk_fma_f32 v[88:89], v[4:5], v[144:145], v[88:89] op_sel:[1,0,0] op_sel_hi:[1,1,1]
	v_pk_fma_f32 v[90:91], v[6:7], v[148:149], v[90:91] op_sel:[1,0,0] op_sel_hi:[1,1,1]
	v_pk_add_f32 v[102:103], v[88:89], v[90:91]
	s_waitcnt lgkmcnt(7)
	v_pk_mul_f32 v[96:97], v[86:87], v[154:155] op_sel:[0,0] op_sel_hi:[0,1]
	v_pk_mul_f32 v[98:99], v[86:87], v[156:157] op_sel:[0,0] op_sel_hi:[0,1]
	v_add_f32_dpp v93, v102, v102 quad_perm:[1,0,3,2] row_mask:0xf bank_mask:0xf
	s_waitcnt vmcnt(6)
	v_pk_fma_f32 v[96:97], v[4:5], v[182:183], v[96:97]
	v_pk_fma_f32 v[98:99], v[6:7], v[184:185], v[98:99]
	v_add_f32_dpp v92, v93, v93 quad_perm:[2,3,0,1] row_mask:0xf bank_mask:0xf
	s_nop 1
	v_add_f32_dpp v93, v92, v92 row_ror:4 row_mask:0xf bank_mask:0xf
	s_nop 1
	v_add_f32_dpp v94, v93, v93 row_ror:8 row_mask:0xf bank_mask:0xf
	v_add_f32_dpp v111, v93, v93 row_ror:8 row_mask:0xf bank_mask:0x2
	s_waitcnt lgkmcnt(6)
	v_pk_fma_f32 v[4:5], v[94:95], v[150:151], v[96:97] op_sel_hi:[0,1,1] neg_lo:[1,0,0] neg_hi:[1,0,0]
	v_pk_fma_f32 v[6:7], v[94:95], v[152:153], v[98:99] op_sel_hi:[0,1,1] neg_lo:[1,0,0] neg_hi:[1,0,0]
	global_load_dwordx4 v[178:181], v0, s[24:25] offset:1280
	s_waitcnt lgkmcnt(4)
	v_pk_mul_f32 v[88:89], v[4:5], v[44:45] op_sel_hi:[0,1]
	v_pk_mul_f32 v[90:91], v[6:7], v[48:49] op_sel_hi:[0,1]
	v_pk_fma_f32 v[88:89], v[4:5], v[46:47], v[88:89] op_sel:[1,0,0] op_sel_hi:[1,1,1]
	v_pk_fma_f32 v[90:91], v[6:7], v[50:51], v[90:91] op_sel:[1,0,0] op_sel_hi:[1,1,1]
	v_pk_add_f32 v[132:133], v[88:89], v[90:91]
	s_waitcnt lgkmcnt(3)
	v_pk_mul_f32 v[96:97], v[86:87], v[56:57] op_sel:[1,0] op_sel_hi:[1,1]
	v_pk_mul_f32 v[98:99], v[86:87], v[58:59] op_sel:[1,0] op_sel_hi:[1,1]
	v_add_f32_dpp v93, v132, v132 quad_perm:[1,0,3,2] row_mask:0xf bank_mask:0xf
	s_waitcnt vmcnt(6)
	v_pk_fma_f32 v[96:97], v[4:5], v[186:187], v[96:97]
	v_pk_fma_f32 v[98:99], v[6:7], v[188:189], v[98:99]
	v_add_f32_dpp v92, v93, v93 quad_perm:[2,3,0,1] row_mask:0xf bank_mask:0xf
	s_nop 1
	v_add_f32_dpp v93, v92, v92 row_ror:4 row_mask:0xf bank_mask:0xf
	s_nop 1
	v_add_f32_dpp v94, v93, v93 row_ror:8 row_mask:0xf bank_mask:0xf
	v_add_f32_dpp v111, v93, v93 row_ror:8 row_mask:0xf bank_mask:0x8
	s_waitcnt lgkmcnt(2)
	v_pk_fma_f32 v[4:5], v[94:95], v[52:53], v[96:97] op_sel_hi:[0,1,1] neg_lo:[1,0,0] neg_hi:[1,0,0]
	v_pk_fma_f32 v[6:7], v[94:95], v[54:55], v[98:99] op_sel_hi:[0,1,1] neg_lo:[1,0,0] neg_hi:[1,0,0]
	global_load_dwordx4 v[182:185], v0, s[24:25] offset:1536
	v_add_f32_dpp v103, v103, v103 row_ror:8 row_mask:0xf bank_mask:0x3
	s_nop 1
	v_add_f32_dpp v103, v133, v133 row_ror:8 row_mask:0xf bank_mask:0xc
	v_add_f32_dpp v135, v135, v135 row_half_mirror row_mask:0xf bank_mask:0x5
	s_nop 1
	v_add_f32_dpp v135, v103, v103 row_half_mirror row_mask:0xf bank_mask:0xa
	v_cndmask_b32_e64 v106, v135, v105, s[36:37]
	v_cndmask_b32_e64 v107, v105, v135, s[36:37]
	s_nop 1
	v_add_f32_dpp v105, v106, v107 quad_perm:[2,3,0,1] row_mask:0xf bank_mask:0xf
	v_cndmask_b32_e64 v106, v105, v101, s[34:35]
	v_cndmask_b32_e64 v107, v101, v105, s[34:35]
	s_nop 1
	v_add_f32_dpp v101, v106, v107 quad_perm:[1,0,3,2] row_mask:0xf bank_mask:0xf
	v_cndmask_b32_e64 v106, v108, v110, s[34:35]
	v_cndmask_b32_e64 v107, v109, v111, s[34:35]
	v_cndmask_b32_e64 v106, v106, v107, s[36:37]
	s_waitcnt lgkmcnt(0)
	v_fma_f32 v101, v112, v115, v101
	v_fma_f32 v101, -v106, v114, v101
	v_cvt_pk_bf16_f32 v107, v101, v101
	global_store_short v16, v107, s[30:31]
	v_lshlrev_b32_e32 v36, 16, v24
	v_lshlrev_b32_e32 v37, 16, v30
	v_and_b32_e32 v38, 0xffff0000, v24
	v_and_b32_e32 v39, 0xffff0000, v30
	ds_write_b128 v2, v[36:39] offset:256
	v_lshlrev_b32_e32 v40, 16, v25
	v_lshlrev_b32_e32 v41, 16, v31
	v_and_b32_e32 v42, 0xffff0000, v25
	v_and_b32_e32 v43, 0xffff0000, v31
	ds_write_b128 v2, v[40:43] offset:512
	v_lshlrev_b32_e32 v44, 16, v26
	v_and_b32_e32 v45, 0xffff0000, v26
	v_lshlrev_b32_e32 v46, 16, v27
	v_and_b32_e32 v47, 0xffff0000, v27
	ds_write_b128 v2, v[44:47] offset:768
	v_lshlrev_b32_e32 v48, 16, v28
	v_and_b32_e32 v49, 0xffff0000, v28
	v_lshlrev_b32_e32 v50, 16, v29
	v_and_b32_e32 v51, 0xffff0000, v29
	ds_write_b128 v2, v[48:51] offset:1024
	v_lshlrev_b32_e32 v52, 16, v32
	s_cmp_eq_u32 s41, 2
	s_cselect_b32 s2, 0, -1
	v_and_b32_e32 v52, s2, v52
	ds_write_b32 v8, v52 offset:0
	s_mov_b32 s2, 0x00010001
	s_mov_b32 s3, 0x00010001
	s_mov_b64 exec, s[2:3]
	ds_write_b64 v9, v[34:35] offset:0
	s_mov_b64 exec, -1
	s_add_u32 s24, s24, 0x1000
	s_addc_u32 s25, s25, 0
	s_add_u32 s26, s26, 0x2800
	s_addc_u32 s27, s27, 0
	s_add_u32 s28, s28, 0x100
	s_addc_u32 s29, s29, 0
	s_add_u32 s30, s30, s40
	s_addc_u32 s31, s31, 0
	s_waitcnt lgkmcnt(0)
	s_barrier
	s_add_u32 s38, s38, 1
	s_cmp_lt_u32 s38, 64
	s_cbranch_scc1 .Lsc_loop
	s_cmp_lg_u32 s41, 0
	s_cbranch_scc1 .Lsc_done
	s_mul_i32 s2, s78, 0xaaab
	s_lshr_b32 s2, s2, 19
	s_lshl_b32 s2, s2, 14
	s_add_u32 s2, s2, 0xff4c000
	s_add_u32 s2, s46, s2
	s_addc_u32 s3, s47, 0
	v_lshl_add_u32 v17, v18, 8, v0
	s_nop 4
	global_store_dwordx4 v17, v[4:7], s[2:3]
